# attention: counted lgkmcnt waits + phase barriers with waves 4-7 one phase behind; GEMM: setprio moved off the barrier-to-MFMA path
# speedup vs baseline: 1.0013x; 1.0013x over previous
; __device__ __forceinline__ void attn_unit(const bf16* __restrict__ qkvb, int seq, int q0, int h, ldsp_t ldsb, float* wsc, const float* tab, float lam) {
;   int tid_ = threadIdx.x; asm volatile("" : "+v"(tid_));
;   const int tid = tid_, wid = __builtin_amdgcn_readfirstlane(tid >> 6), lane = tid & 63, r32 = lane & 31, hi = lane >> 5, mapw = wid >> 2, rg = wid & 3;
;   float* ws = wsc + wid * 64; float* li_l = ws; float* al_l = ws + 32;
;   float m_reg = -1e30f, l_reg = 0; bf16x8 qr[8]; f32x16 o[8];
; #pragma unroll
;   for (int d = 0; d < 8; ++d) o[d] = f32x16{};
;   const int q0w = q0 + rg * 32;
;   const bf16* Qw = qkvb + (long)(q0w + r32) * LD + h * 256 + mapw * 128 + hi * 8;
; #pragma unroll
;   for (int d0 = 0; d0 < 8; ++d0) qr[d0] = *reinterpret_cast<const bf16x8*>(Qw + d0 * 16);
;   unsigned koff0, voff0;
;   { const int row = 4 * wid + (lane >> 4), c = (lane & 15) ^ (row & 15); koff0 = (unsigned)(row * LD + 2048 + h * 256 + c * 8) * 2u; }
;   { const int subt = 2 * wid + (lane >> 5), kk = ((subt >> 3) << 3) | ((lane & 31) >> 2), key = (kk & ~0xC) | ((kk & 4) << 1) | ((kk & 8) >> 1), col = (subt & 7) * 32 + 8 * (lane & 3);
;     voff0 = (unsigned)(key * LD + 4096 + h * 256 + col) * 2u; }
;   const char* kvb = (const char*)qkvb;
;   const long tstep = 64L * LD * 2;
;     ...
;   const int NT = seq / 64;
;   const float cL = __int_as_float(__builtin_amdgcn_readfirstlane(__float_as_int(tab[0]))), cR = __int_as_float(__builtin_amdgcn_readfirstlane(__float_as_int(tab[256])));
;   ldsc_t kp[4];
; #pragma unroll
;   for (int d = 0; d < 4; ++d) kp[d] = (ldsc_t)ldsb + (mapw * 16384 + r32 * 256 + ((d * 32 + hi * 16) ^ ((r32 & 15) << 4)));
;   const int kd = (r32 & 8) ? -128 : 128;
;   const ldsc_t vp = (ldsc_t)ldsb + (V_OFF + v_rd_base(lane));
;   { _Pragma("unroll") for (int i = 0; i < 4; ++i) { DMA_K1(kvb, 0, i); DMA_V1(kvb, 0, i); } }
; __global__ void __launch_bounds__(NWAVES * 64, 2) fwd_kernel(Args args) {
;     ...
;                 const int uid = ui * F.G + F.vcu; if (uid >= Bc * 8 * nqb) break;
;                 const int bh = uid >> lgN2, qb = uid & (nqb - 1), b = bh >> 3, h = bh & 7;
;                 att3::attn_unit((const att3::bf16*)P_QKV + (size_t)b * S * QKVW, S, qb * 128, h, F.lds + RING_OFF, (float*)(lds + WSC_OFF), (const float*)(lds + TAB_OFF) + h * 260, lamfull);
.LBB0_546:
	s_mul_i32 s6, s13, s97
	s_add_i32 s6, s6, s33
	s_cmp_ge_i32 s6, s10
	s_mov_b64 s[4:5], -1
	s_cbranch_scc1 .LBB0_545
	s_ashr_i32 s5, s6, s42
	s_and_b32 s14, s6, s51
	s_mov_b32 s6, 22
	s_ashr_i32 s7, s6, 31
	s_ashr_i32 s4, s5, 3
	s_and_b32 s18, s5, 7
	s_lshl_b64 s[6:7], s[6:7], 3
	s_add_u32 s6, s0, s6
	s_addc_u32 s7, s1, s7
	s_load_dwordx2 s[8:9], s[6:7], 0x0
	s_ashr_i32 s5, s4, 31
	s_lshl_b64 s[6:7], s[4:5], s43
	s_mul_i32 s4, s7, 0x3000
	s_mul_hi_u32 s5, s6, 0x3000
	s_add_i32 s5, s5, s4
	s_mul_i32 s4, s6, 0x3000
	v_mov_b32_e32 v1, v245
	s_waitcnt lgkmcnt(0)
	s_add_u32 s8, s8, s4
	s_addc_u32 s9, s9, s5
	v_readfirstlane_b32 s16, v1
	s_mul_i32 s4, s18, 0x410
	s_ashr_i32 s24, s16, 6
	s_add_i32 s20, s4, 0
	s_lshl_b32 s4, s24, 5
	s_lshl_b32 s14, s14, 7
	s_and_b32 s17, s4, 0x60
	v_and_b32_e32 v247, 31, v1
	s_or_b32 s21, s17, s14
	v_or_b32_e32 v2, s21, v247
	v_mul_u32_u24_e32 v2, 0x1800, v2
	s_ashr_i32 s25, s16, 8
	v_lshlrev_b32_e32 v226, 1, v2
	v_lshl_add_u64 v[2:3], s[8:9], 0, v[226:227]
	s_lshl_b32 s84, s18, 9
	s_lshl_b32 s4, s25, 7
	v_lshl_add_u64 v[2:3], v[2:3], 0, s[84:85]
	s_ashr_i32 s5, s4, 31
	v_lshl_add_u64 v[2:3], s[4:5], 1, v[2:3]
	s_lshl_b32 s4, s24, 2
	v_bfe_u32 v10, v1, 4, 2
	v_bfe_u32 v248, v1, 5, 1
	v_bitop3_b32 v5, s4, v1, v10 bitop3:0x36
	v_lshlrev_b32_e32 v236, 4, v248
	v_mov_b32_e32 v237, v227
	v_or_b32_e32 v4, s4, v10
	v_lshlrev_b32_e32 v5, 3, v5
	s_lshl_b32 s4, s24, 1
	s_lshl_b32 s15, s18, 8
	v_lshl_add_u64 v[2:3], v[2:3], 0, v[236:237]
	v_mul_lo_u32 v4, v4, s67
	v_and_b32_e32 v11, 0x78, v5
	s_and_b32 s5, s4, 0x1ffff0
	v_lshrrev_b32_e32 v5, 1, v1
	v_or3_b32 v6, v4, v11, s15
	v_bfe_u32 v4, v1, 2, 2
	s_and_b32 s18, s24, 4
	global_load_dwordx4 v[162:165], v[2:3], off offset:224
	global_load_dwordx4 v[166:169], v[2:3], off offset:192
	global_load_dwordx4 v[170:173], v[2:3], off offset:160
	global_load_dwordx4 v[174:177], v[2:3], off offset:128
	global_load_dwordx4 v[178:181], v[2:3], off offset:96
	global_load_dwordx4 v[182:185], v[2:3], off offset:64
	global_load_dwordx4 v[186:189], v[2:3], off offset:32
	global_load_dwordx4 v[190:193], v[2:3], off
	v_and_or_b32 v2, v5, 8, s5
	v_or3_b32 v2, s18, v4, v2
	v_and_or_b32 v7, s4, 6, v248
	v_lshlrev_b32_e32 v8, 3, v1
	v_mul_u32_u24_e32 v2, 0x1800, v2
	s_lshl_b32 s4, s24, 10
	s_add_i32 s20, s20, 0x20a00
	v_lshlrev_b32_e32 v7, 5, v7
	v_and_b32_e32 v12, 24, v8
	v_or_b32_e32 v13, s15, v2
	v_mov_b32_e32 v15, 0x1000
	s_add_i32 s23, s4, 0
	v_or3_b32 v2, v7, v12, v13
	v_mov_b32_e32 v14, 0x2000
	v_mov_b32_e32 v3, s20
	v_lshl_add_u32 v226, v6, 1, v15
	s_mov_b32 m0, s23
	v_lshl_add_u32 v2, v2, 1, v14
	ds_read2st64_b32 v[4:5], v3 offset1:4
	v_lshl_add_u64 v[6:7], s[8:9], 0, v[226:227]
	v_mov_b32_e32 v3, v227
	global_load_lds_dwordx4 v226, s[8:9]
	s_add_i32 m0, s23, 0x8000
	v_lshl_add_u64 v[8:9], s[8:9], 0, v[2:3]
	global_load_lds_dwordx4 v2, s[8:9]
	v_lshl_add_u64 v[2:3], v[6:7], 0, s[90:91]
	s_add_i32 m0, s23, 0x2000
	s_mov_b64 s[4:5], 0x30000
	global_load_lds_dwordx4 v[2:3], off
	v_lshl_add_u64 v[2:3], v[8:9], 0, s[4:5]
	s_add_i32 m0, s23, 0xa000
	s_mov_b64 s[4:5], 0x100
	global_load_lds_dwordx4 v[2:3], off
	v_lshl_add_u64 v[2:3], v[6:7], 0, s[4:5]
	s_add_i32 m0, s23, 0x4000
	s_mov_b64 s[4:5], 0x60100
	global_load_lds_dwordx4 v[2:3], off
	v_lshl_add_u64 v[2:3], v[8:9], 0, s[90:91]
	s_add_i32 m0, s23, 0xc000
	s_waitcnt lgkmcnt(0)
	v_readfirstlane_b32 s19, v4
	global_load_lds_dwordx4 v[2:3], off
	v_lshl_add_u64 v[2:3], v[6:7], 0, s[4:5]
	s_add_i32 m0, s23, 0x6000
	s_mov_b64 s[4:5], 0x90000
	global_load_lds_dwordx4 v[2:3], off
	v_lshl_add_u64 v[2:3], v[8:9], 0, s[4:5]
	s_add_i32 m0, s23, 0xe000
	s_and_b32 s4, s16, 0x3fffffc0
	global_load_lds_dwordx4 v[2:3], off
	s_lshl_b32 s4, s4, 2
	s_add_i32 s18, s4, 0
	s_lshl_b32 s4, s25, 14
	v_lshlrev_b32_e32 v3, 4, v1
	s_add_i32 s4, s4, 0
	v_readfirstlane_b32 s22, v5
	v_and_b32_e32 v4, 0xf0, v3
	v_lshl_add_u32 v5, v247, 8, s4
	v_or_b32_e32 v6, 32, v236
	v_xad_u32 v253, v6, v4, v5
	v_or_b32_e32 v6, 64, v236
	v_and_b32_e32 v2, 63, v1
	v_xad_u32 v241, v6, v4, v5
	v_or_b32_e32 v6, 0x60, v236
	v_xad_u32 v252, v236, v4, v5
	v_xad_u32 v244, v6, v4, v5
	v_lshlrev_b32_e32 v5, 3, v2
	s_and_b32 s4, s24, 3
	v_and_b32_e32 v6, 24, v5
	v_and_b32_e32 v3, 0xc0, v3
	v_lshlrev_b32_e32 v7, 1, v1
	s_lshl_b32 s5, s4, 5
	v_and_b32_e32 v4, 8, v1
	v_and_b32_e32 v7, 32, v7
	v_and_b32_e32 v5, 0x100, v5
	v_add3_u32 v3, 0, v6, v3
	s_or_b32 s5, s5, s14
	v_add3_u32 v250, v3, v7, v5
	v_cmp_eq_u32_e32 vcc, 0, v4
	v_mov_b32_e32 v3, 0xffffff80
	v_mov_b32_e32 v4, 0x80
	s_sub_i32 s26, 0, s5
	s_mul_i32 s5, s24, 0x6000
	v_cndmask_b32_e32 v251, v3, v4, vcc
	v_cmp_gt_u32_e32 vcc, 32, v2
	v_mov_b32_e32 v2, s5
	v_mad_u32_u24 v2, v10, s67, v2
	v_or3_b32 v2, v2, s15, v11
	v_lshl_add_u32 v226, v2, 1, v15
	v_lshl_or_b32 v2, s4, 6, v13
	v_and_b32_e32 v1, 32, v1
	s_waitcnt vmcnt(0)
	s_waitcnt vmcnt(0)
; __device__ __forceinline__ int v_rd_base(int lane) { return ((lane & 3) << 3) | (((lane >> 2) & 3) << 6) | (((lane >> 4) & 1) << 5) | (((lane >> 5) & 1) << 8); }
; #define DMA_K1(g_, b, i_) __builtin_amdgcn_global_load_lds((const unsigned*)((g_) + (((i_) & 1) * 32 * LD * 2 + ((i_) >> 1) * 256) + koff0), (__attribute__((address_space(3))) unsigned*)(ldsb + (b) * STAGE + (wid + 8 * (i_)) * 1024), 16, 0, 0)
; __device__ __forceinline__ void attn_unit(const bf16* __restrict__ qkvb, int seq, int q0, int h, ldsp_t ldsb, float* wsc, const float* tab, float lam) {
;     ...
;   float m_reg = -1e30f, l_reg = 0; bf16x8 qr[8]; f32x16 o[8];
; #pragma unroll
;   for (int d = 0; d < 8; ++d) o[d] = f32x16{};
;   const int q0w = q0 + rg * 32;
;   const bf16* Qw = qkvb + (long)(q0w + r32) * LD + h * 256 + mapw * 128 + hi * 8;
; #pragma unroll
;   for (int d0 = 0; d0 < 8; ++d0) qr[d0] = *reinterpret_cast<const bf16x8*>(Qw + d0 * 16);
;   unsigned koff0, voff0;
;   { const int row = 4 * wid + (lane >> 4), c = (lane & 15) ^ (row & 15); koff0 = (unsigned)(row * LD + 2048 + h * 256 + c * 8) * 2u; }
;   { const int subt = 2 * wid + (lane >> 5), kk = ((subt >> 3) << 3) | ((lane & 31) >> 2), key = (kk & ~0xC) | ((kk & 4) << 1) | ((kk & 8) >> 1), col = (subt & 7) * 32 + 8 * (lane & 3);
;     voff0 = (unsigned)(key * LD + 4096 + h * 256 + col) * 2u; }
;   const char* kvb = (const char*)qkvb;
;   const long tstep = 64L * LD * 2;
;     ...
;   const int NT = seq / 64;
;   const float cL = __int_as_float(__builtin_amdgcn_readfirstlane(__float_as_int(tab[0]))), cR = __int_as_float(__builtin_amdgcn_readfirstlane(__float_as_int(tab[256])));
;   ldsc_t kp[4];
; #pragma unroll
;   for (int d = 0; d < 4; ++d) kp[d] = (ldsc_t)ldsb + (mapw * 16384 + r32 * 256 + ((d * 32 + hi * 16) ^ ((r32 & 15) << 4)));
;   const int kd = (r32 & 8) ? -128 : 128;
;   const ldsc_t vp = (ldsc_t)ldsb + (V_OFF + v_rd_base(lane));
;   { _Pragma("unroll") for (int i = 0; i < 4; ++i) { DMA_K1(kvb, 0, i); DMA_V1(kvb, 0, i); } }
;   asm volatile("s_waitcnt vmcnt(0)" : "+v"(qr[0]), "+v"(qr[1]), "+v"(qr[2]), "+v"(qr[3]), "+v"(qr[4]), "+v"(qr[5]), "+v"(qr[6]), "+v"(qr[7]) :: "memory");
;   for (int j = 0; j < NT; ++j) {
	v_lshlrev_b32_e32 v3, 2, v248
	v_or3_b32 v1, v2, v1, v12
	v_mov_b32_e32 v98, v227
	v_mov_b32_e32 v99, v227
	v_mov_b32_e32 v112, v227
	v_mov_b32_e32 v113, v227
	v_mov_b32_e32 v0, v245
	s_add_i32 s18, s18, 0x20200
	v_sub_u32_e32 v245, v3, v247
	v_lshl_add_u32 v238, v1, 1, v14
	v_mov_b32_e32 v100, v227
	v_mov_b32_e32 v101, v227
	v_mov_b32_e32 v102, v227
	v_mov_b32_e32 v103, v227
	v_mov_b32_e32 v104, v227
	v_mov_b32_e32 v105, v227
	v_mov_b32_e32 v106, v227
	v_mov_b32_e32 v107, v227
	v_mov_b32_e32 v108, v227
	v_mov_b32_e32 v109, v227
	v_mov_b32_e32 v110, v227
	v_mov_b32_e32 v111, v227
	v_mov_b64_e32 v[128:129], v[112:113]
	v_mov_b64_e32 v[66:67], v[98:99]
	v_mov_b64_e32 v[82:83], v[98:99]
	v_mov_b64_e32 v[34:35], v[98:99]
	v_mov_b64_e32 v[50:51], v[98:99]
	v_mov_b64_e32 v[18:19], v[98:99]
	v_mov_b64_e32 v[2:3], v[98:99]
	v_mov_b32_e32 v242, 0x80008000
	v_mov_b32_e32 v246, 0x260
	v_mov_b32_e32 v240, 0x3727c5ac
	s_mov_b32 s25, 0
	v_lshl_add_u32 v237, v247, 2, s18
	v_mov_b32_e32 v239, v227
	v_mov_b32_e32 v249, 0
	v_mov_b32_e32 v211, 0xf149f2ca
	s_mov_b32 s27, 0x10000
	v_mov_b64_e32 v[126:127], v[110:111]
	v_mov_b64_e32 v[124:125], v[108:109]
	v_mov_b64_e32 v[122:123], v[106:107]
	v_mov_b64_e32 v[120:121], v[104:105]
	v_mov_b64_e32 v[118:119], v[102:103]
	v_mov_b64_e32 v[116:117], v[100:101]
	v_mov_b64_e32 v[114:115], v[98:99]
	v_mov_b64_e32 v[68:69], v[100:101]
	v_mov_b64_e32 v[70:71], v[102:103]
	v_mov_b64_e32 v[72:73], v[104:105]
	v_mov_b64_e32 v[74:75], v[106:107]
	v_mov_b64_e32 v[76:77], v[108:109]
	v_mov_b64_e32 v[78:79], v[110:111]
	v_mov_b64_e32 v[80:81], v[112:113]
	v_mov_b64_e32 v[84:85], v[100:101]
	v_mov_b64_e32 v[86:87], v[102:103]
	v_mov_b64_e32 v[88:89], v[104:105]
	v_mov_b64_e32 v[90:91], v[106:107]
	v_mov_b64_e32 v[92:93], v[108:109]
	v_mov_b64_e32 v[94:95], v[110:111]
	v_mov_b64_e32 v[96:97], v[112:113]
	v_mov_b64_e32 v[36:37], v[100:101]
	v_mov_b64_e32 v[38:39], v[102:103]
	v_mov_b64_e32 v[40:41], v[104:105]
	v_mov_b64_e32 v[42:43], v[106:107]
	v_mov_b64_e32 v[44:45], v[108:109]
	v_mov_b64_e32 v[46:47], v[110:111]
	v_mov_b64_e32 v[48:49], v[112:113]
	v_mov_b64_e32 v[52:53], v[100:101]
	v_mov_b64_e32 v[54:55], v[102:103]
	v_mov_b64_e32 v[56:57], v[104:105]
	v_mov_b64_e32 v[58:59], v[106:107]
	v_mov_b64_e32 v[60:61], v[108:109]
	v_mov_b64_e32 v[62:63], v[110:111]
	v_mov_b64_e32 v[64:65], v[112:113]
	v_mov_b64_e32 v[20:21], v[100:101]
	v_mov_b64_e32 v[22:23], v[102:103]
	v_mov_b64_e32 v[24:25], v[104:105]
	v_mov_b64_e32 v[26:27], v[106:107]
	v_mov_b64_e32 v[28:29], v[108:109]
	v_mov_b64_e32 v[30:31], v[110:111]
	v_mov_b64_e32 v[32:33], v[112:113]
	v_mov_b64_e32 v[4:5], v[100:101]
	v_mov_b64_e32 v[6:7], v[102:103]
	v_mov_b64_e32 v[8:9], v[104:105]
	v_mov_b64_e32 v[10:11], v[106:107]
	v_mov_b64_e32 v[12:13], v[108:109]
	v_mov_b64_e32 v[14:15], v[110:111]
	v_mov_b64_e32 v[16:17], v[112:113]
	s_cmp_lt_u32 s18, 0x20600
	s_cbranch_scc1 .Lpp_skip_y
	s_barrier
; #define SBAR() __builtin_amdgcn_sched_barrier(0)
; #define KF(a, o) (*(const __attribute__((address_space(3))) bf16x8*)((a) + (o)))
; template <class Hook> __device__ __forceinline__ void qk_sub(f32x16& p, ldsc_t k0, ldsc_t k1, ldsc_t k2, ldsc_t k3, int kd, const bf16x8* qr, const Hook& hook) {
;     ...
;   SBAR();
;   bf16x8 f0 = KF(k0, 0), f1 = KF(k1, 0), f2 = KF(k2, 0), f3 = KF(k3, 0); SBAR(); __builtin_amdgcn_s_setprio(1);
;   p = __builtin_amdgcn_mfma_f32_32x32x16_bf16(f0, qr[0], f32x16{}, 0, 0, 0); f0 = KF(k0 + kd, 0); SBAR();
;   p = __builtin_amdgcn_mfma_f32_32x32x16_bf16(f1, qr[1], p, 0, 0, 0); f1 = KF(k1 + kd, 0); hook(0); SBAR();
;   p = __builtin_amdgcn_mfma_f32_32x32x16_bf16(f2, qr[2], p, 0, 0, 0); f2 = KF(k2 + kd, 0); SBAR();
;   p = __builtin_amdgcn_mfma_f32_32x32x16_bf16(f3, qr[3], p, 0, 0, 0); f3 = KF(k3 + kd, 0); hook(1); SBAR();
;   p = __builtin_amdgcn_mfma_f32_32x32x16_bf16(f0, qr[4], p, 0, 0, 0); SBAR();
;   p = __builtin_amdgcn_mfma_f32_32x32x16_bf16(f1, qr[5], p, 0, 0, 0); hook(2); SBAR();
;   p = __builtin_amdgcn_mfma_f32_32x32x16_bf16(f2, qr[6], p, 0, 0, 0); SBAR();
;   p = __builtin_amdgcn_mfma_f32_32x32x16_bf16(f3, qr[7], p, 0, 0, 0); hook(3); __builtin_amdgcn_s_setprio(0); SBAR();
; __device__ __forceinline__ void softmax_sub(f32x16& p, float& m_reg, float& l_reg, bf16x8& pa0, bf16x8& pa1, f32x16 (&o)[8], float* al_l, int r32, int hi, int dj, const float* tab, float cL, float cR) {
;     ...
;   if (dj <= -159) cb = cL;
;   else if (dj >= 159) cb = cR;
;   else { cb = 0.f; const int ib = dj - r32 + 4 * hi + 128;
; #pragma unroll
;     for (int r = 0; r < 16; ++r) { const int i0 = ib + (r & 3) + 8 * (r >> 2); p[r] += tab[min(max(i0, 0), 256)]; } }
.Lpp_skip_y:
.LBB0_548:
	s_waitcnt vmcnt(0)
	s_add_i32 s4, s27, 0xffff0000
	s_barrier
	s_and_b32 s29, s4, 0x10000
	v_add_u32_e32 v1, s29, v252
	v_add_u32_e32 v198, s29, v253
	v_add_u32_e32 v199, s29, v241
	v_add_u32_e32 v202, s29, v244
	ds_read_b128 v[130:133], v1
	ds_read_b128 v[134:137], v198
	ds_read_b128 v[138:141], v199
	ds_read_b128 v[142:145], v202
	s_setprio 1
	s_waitcnt lgkmcnt(3)
	v_mfma_f32_32x32x16_bf16 v[146:161], v[130:133], v[190:193], 0
	v_add_u32_e32 v206, v1, v251
	ds_read_b128 v[130:133], v206
	s_and_b32 s24, s27, 0x10000
	s_add_i32 s28, s23, s24
	v_lshl_add_u64 v[194:195], s[8:9], 0, v[226:227]
	v_add_u32_e32 v210, v198, v251
	v_lshl_add_u64 v[196:197], v[194:195], 0, s[92:93]
	s_mov_b32 m0, s28
	s_waitcnt lgkmcnt(3)
	v_mfma_f32_32x32x16_bf16 v[146:161], v[134:137], v[186:189], v[146:161]
	ds_read_b128 v[134:137], v210
	global_load_lds_dwordx4 v[196:197], off
	s_waitcnt lgkmcnt(3)
	v_mfma_f32_32x32x16_bf16 v[146:161], v[138:141], v[182:185], v[146:161]
	v_add_u32_e32 v212, v199, v251
	ds_read_b128 v[138:141], v212
	v_add_u32_e32 v213, v202, v251
	s_add_i32 m0, s28, 0x2000
	v_lshl_add_u64 v[196:197], v[194:195], 0, s[94:95]
	s_waitcnt lgkmcnt(3)
	v_mfma_f32_32x32x16_bf16 v[146:161], v[142:145], v[178:181], v[146:161]
	ds_read_b128 v[142:145], v213
	global_load_lds_dwordx4 v[196:197], off
	s_waitcnt lgkmcnt(3)
	v_mfma_f32_32x32x16_bf16 v[146:161], v[130:133], v[174:177], v[146:161]
	s_mov_b64 s[4:5], 0xc0100
	s_add_i32 m0, s28, 0x4000
	v_lshl_add_u64 v[130:131], v[194:195], 0, s[4:5]
	global_load_lds_dwordx4 v[130:131], off
	s_waitcnt lgkmcnt(2)
	v_mfma_f32_32x32x16_bf16 v[146:161], v[134:137], v[170:173], v[146:161]
	s_waitcnt lgkmcnt(1)
	v_mfma_f32_32x32x16_bf16 v[146:161], v[138:141], v[166:169], v[146:161]
	s_mov_b64 s[4:5], 0x120100
	s_add_i32 m0, s28, 0x6000
	v_lshl_add_u64 v[130:131], v[194:195], 0, s[4:5]
	global_load_lds_dwordx4 v[130:131], off
	s_waitcnt lgkmcnt(0)
	v_mfma_f32_32x32x16_bf16 v[146:161], v[142:145], v[162:165], v[146:161]
	s_setprio 0
	ds_read_b128 v[130:133], v1 offset:8192
	ds_read_b128 v[194:197], v198 offset:8192
	ds_read_b128 v[198:201], v199 offset:8192
	ds_read_b128 v[202:205], v202 offset:8192
	s_setprio 1
	s_waitcnt lgkmcnt(3)
	v_mfma_f32_32x32x16_bf16 v[130:145], v[130:133], v[190:193], 0
	ds_read_b128 v[206:209], v206 offset:8192
	s_waitcnt lgkmcnt(3)
	v_mfma_f32_32x32x16_bf16 v[130:145], v[194:197], v[186:189], v[130:145]
	ds_read_b128 v[194:197], v210 offset:8192
	s_waitcnt lgkmcnt(3)
	v_mfma_f32_32x32x16_bf16 v[130:145], v[198:201], v[182:185], v[130:145]
	ds_read_b128 v[198:201], v212 offset:8192
	s_waitcnt lgkmcnt(3)
	v_mfma_f32_32x32x16_bf16 v[130:145], v[202:205], v[178:181], v[130:145]
	ds_read_b128 v[202:205], v213 offset:8192
	s_waitcnt lgkmcnt(3)
	v_mfma_f32_32x32x16_bf16 v[130:145], v[206:209], v[174:177], v[130:145]
	s_waitcnt lgkmcnt(2)
	v_mfma_f32_32x32x16_bf16 v[130:145], v[194:197], v[170:173], v[130:145]
	s_waitcnt lgkmcnt(1)
	v_mfma_f32_32x32x16_bf16 v[130:145], v[198:201], v[166:169], v[130:145]
	s_waitcnt lgkmcnt(0)
	v_mfma_f32_32x32x16_bf16 v[130:145], v[202:205], v[162:165], v[130:145]
	s_setprio 0
	s_barrier
	v_add_u32_e32 v1, s29, v250
	ds_read_b64_tr_b16 v[206:207], v1 offset:32768
	ds_read_b64_tr_b16 v[208:209], v1 offset:36864
	ds_read_b64_tr_b16 v[200:201], v1 offset:37376
	ds_read_b64_tr_b16 v[198:199], v1 offset:33280
	ds_read_b64_tr_b16 v[202:203], v1 offset:40960
	ds_read_b64_tr_b16 v[204:205], v1 offset:45056
	ds_read_b64_tr_b16 v[196:197], v1 offset:45568
	ds_read_b64_tr_b16 v[194:195], v1 offset:41472
	s_cmpk_lt_i32 s26, 0xff62
	s_cbranch_scc1 .LBB0_551
	s_cmpk_gt_i32 s26, 0x9e
	s_cbranch_scc1 .LBB0_552
	v_add_u32_e32 v210, s26, v245
	v_add_u32_e32 v210, 0x80, v210
	v_mov_b32_e32 v212, 0x100
	v_med3_i32 v212, v210, 0, v212
	v_lshl_add_u32 v220, v212, 2, s20
	v_max_i32_e32 v212, -1, v210
	v_add_u32_e32 v212, 1, v212
	v_min_u32_e32 v212, 0x100, v212
	v_lshl_add_u32 v221, v212, 2, s20
	v_max_i32_e32 v212, -2, v210
	v_add_u32_e32 v212, 2, v212
	v_min_u32_e32 v212, 0x100, v212
	v_lshl_add_u32 v222, v212, 2, s20
	v_max_i32_e32 v212, -3, v210
	v_add_u32_e32 v212, 3, v212
	v_min_u32_e32 v212, 0x100, v212
	v_lshl_add_u32 v223, v212, 2, s20
	v_max_i32_e32 v212, -8, v210
	v_add_u32_e32 v212, 8, v212
	v_min_u32_e32 v212, 0x100, v212
	v_lshl_add_u32 v224, v212, 2, s20
	v_max_i32_e32 v212, -9, v210
	v_add_u32_e32 v212, 9, v212
	v_min_u32_e32 v212, 0x100, v212
	v_lshl_add_u32 v225, v212, 2, s20
	v_max_i32_e32 v212, -10, v210
	v_add_u32_e32 v212, 10, v212
	v_min_u32_e32 v212, 0x100, v212
	v_lshl_add_u32 v232, v212, 2, s20
	v_max_i32_e32 v212, -11, v210
	v_add_u32_e32 v212, 11, v212
	v_min_u32_e32 v212, 0x100, v212
	v_lshl_add_u32 v233, v212, 2, s20
	v_max_i32_e32 v212, -16, v210
	v_max_i32_e32 v213, 0xffffffef, v210
	v_max_i32_e32 v214, 0xffffffee, v210
	v_max_i32_e32 v215, 0xffffffed, v210
	v_max_i32_e32 v216, 0xffffffe8, v210
	v_max_i32_e32 v217, 0xffffffe7, v210
	v_max_i32_e32 v218, 0xffffffe6, v210
	v_add_u32_e32 v212, 16, v212
	v_add_u32_e32 v213, 17, v213
	v_add_u32_e32 v214, 18, v214
	v_add_u32_e32 v215, 19, v215
	v_add_u32_e32 v216, 24, v216
	v_add_u32_e32 v217, 25, v217
	v_add_u32_e32 v218, 26, v218
	v_max_i32_e32 v210, 0xffffffe5, v210
	v_min_u32_e32 v212, 0x100, v212
	v_min_u32_e32 v213, 0x100, v213
	v_min_u32_e32 v214, 0x100, v214
	v_min_u32_e32 v215, 0x100, v215
	v_min_u32_e32 v216, 0x100, v216
	v_min_u32_e32 v217, 0x100, v217
	v_min_u32_e32 v218, 0x100, v218
	v_add_u32_e32 v210, 27, v210
	v_lshl_add_u32 v212, v212, 2, s20
	v_lshl_add_u32 v213, v213, 2, s20
	v_lshl_add_u32 v214, v214, 2, s20
	v_lshl_add_u32 v215, v215, 2, s20
	v_lshl_add_u32 v216, v216, 2, s20
	v_lshl_add_u32 v217, v217, 2, s20
	v_lshl_add_u32 v218, v218, 2, s20
	v_min_u32_e32 v210, 0x100, v210
	v_lshl_add_u32 v210, v210, 2, s20
	ds_read_b32 v212, v212
	ds_read_b32 v213, v213
	ds_read_b32 v214, v214
	ds_read_b32 v215, v215
	ds_read_b32 v216, v216
	ds_read_b32 v217, v217
	ds_read_b32 v218, v218
	ds_read_b32 v219, v210
	ds_read_b32 v220, v220
	ds_read_b32 v221, v221
	ds_read_b32 v222, v222
	ds_read_b32 v223, v223
	ds_read_b32 v224, v224
	ds_read_b32 v225, v225
	ds_read_b32 v232, v232
	ds_read_b32 v233, v233
	s_waitcnt lgkmcnt(0)
	v_pk_add_f32 v[160:161], v[160:161], v[218:219]
	v_pk_add_f32 v[158:159], v[158:159], v[216:217]
	v_pk_add_f32 v[156:157], v[156:157], v[214:215]
	v_pk_add_f32 v[154:155], v[154:155], v[212:213]
	v_pk_add_f32 v[152:153], v[152:153], v[232:233]
	v_pk_add_f32 v[150:151], v[150:151], v[224:225]
	v_pk_add_f32 v[148:149], v[148:149], v[222:223]
	v_pk_add_f32 v[146:147], v[146:147], v[220:221]
	s_mov_b32 s29, 0
	s_branch .LBB0_553

; #define SBAR() __builtin_amdgcn_sched_barrier(0)
; template <int D0, int S> __device__ __forceinline__ VG vload(ldsc_t vb) { VG g; g.l0 = vtr(vb + v_rd_off(D0, 2 * S, 0)); g.h0 = vtr(vb + v_rd_off(D0, 2 * S, 1)); g.l1 = vtr(vb + v_rd_off(D0, 2 * S + 1, 0)); g.h1 = vtr(vb + v_rd_off(D0, 2 * S + 1, 1)); return g; }
; __device__ __forceinline__ void softmax_sub(f32x16& p, float& m_reg, float& l_reg, bf16x8& pa0, bf16x8& pa1, f32x16 (&o)[8], float* al_l, int r32, int hi, int dj, const float* tab, float cL, float cR) {
;     ...
;   const float mnC = (cb - mn) * C;
;   float ps = 0;
; #pragma unroll
;   for (int r = 0; r < 16; ++r) { p[r] = __builtin_amdgcn_exp2f(fmaf(p[r], C, mnC)); ps += p[r]; }
;   { auto rr = __builtin_amdgcn_permlane32_swap(__float_as_uint(ps), __float_as_uint(ps), false, false);
;     ps = __uint_as_float(rr[0]) + __uint_as_float(rr[1]); }
;   l_reg = l_reg * alpha + ps;
;     ...
;   PK4(p, 0, pa0); PK4(p, 8, pa1);
;     ...
; }
; template <int S, class Dma> __device__ __forceinline__ void pv_run(f32x16 (&o)[8], ldsc_t vb, VG g0, VG g1, bf16x8 pa0, bf16x8 pa1, const Dma& dma) {
;   SBAR(); __builtin_amdgcn_s_setprio(1);
;   vmma(o[0], g0, pa0, pa1); dma(0); SBAR(); g0 = vload<2, S>(vb); SBAR();
;   vmma(o[1], g1, pa0, pa1); dma(1); SBAR(); g1 = vload<3, S>(vb); SBAR();
;   vmma(o[2], g0, pa0, pa1); dma(2); SBAR(); g0 = vload<4, S>(vb); SBAR();
;   vmma(o[3], g1, pa0, pa1); dma(3); SBAR(); g1 = vload<5, S>(vb); SBAR();
;   vmma(o[4], g0, pa0, pa1); dma(4); SBAR(); g0 = vload<6, S>(vb); SBAR();
;   vmma(o[5], g1, pa0, pa1); dma(5); SBAR(); g1 = vload<7, S>(vb); SBAR();
;   vmma(o[6], g0, pa0, pa1); dma(6); SBAR(); vmma(o[7], g1, pa0, pa1); dma(7); __builtin_amdgcn_s_setprio(0); SBAR();
.LBB0_555:
	v_sub_f32_e32 v211, s29, v210
	v_mul_f32_e32 v211, 0x3e0293ee, v211
	v_fmamk_f32 v146, v146, 0x3e0293ee, v211
	v_exp_f32_e32 v146, v146
	v_fmamk_f32 v147, v147, 0x3e0293ee, v211
	v_exp_f32_e32 v147, v147
	v_fmamk_f32 v148, v148, 0x3e0293ee, v211
	v_exp_f32_e32 v148, v148
	v_fmamk_f32 v149, v149, 0x3e0293ee, v211
	v_exp_f32_e32 v149, v149
	v_fmamk_f32 v150, v150, 0x3e0293ee, v211
	v_add_f32_e32 v212, 0, v146
	v_exp_f32_e32 v150, v150
	v_fmamk_f32 v151, v151, 0x3e0293ee, v211
	v_add_f32_e32 v212, v147, v212
	v_exp_f32_e32 v151, v151
	v_fmamk_f32 v152, v152, 0x3e0293ee, v211
	v_add_f32_e32 v212, v148, v212
	v_exp_f32_e32 v152, v152
	v_fmamk_f32 v153, v153, 0x3e0293ee, v211
	v_add_f32_e32 v212, v149, v212
	v_exp_f32_e32 v153, v153
	v_fmamk_f32 v154, v154, 0x3e0293ee, v211
	v_add_f32_e32 v212, v150, v212
	v_exp_f32_e32 v154, v154
	v_fmamk_f32 v155, v155, 0x3e0293ee, v211
	v_add_f32_e32 v212, v151, v212
	v_exp_f32_e32 v155, v155
	v_fmamk_f32 v156, v156, 0x3e0293ee, v211
	v_add_f32_e32 v212, v152, v212
	v_exp_f32_e32 v156, v156
	v_fmamk_f32 v157, v157, 0x3e0293ee, v211
	v_add_f32_e32 v212, v153, v212
	v_exp_f32_e32 v157, v157
	v_fmamk_f32 v158, v158, 0x3e0293ee, v211
	v_add_f32_e32 v212, v154, v212
	v_exp_f32_e32 v158, v158
	v_fmamk_f32 v159, v159, 0x3e0293ee, v211
	v_add_f32_e32 v212, v155, v212
	v_exp_f32_e32 v159, v159
	v_fmamk_f32 v160, v160, 0x3e0293ee, v211
	v_add_f32_e32 v212, v156, v212
	v_exp_f32_e32 v160, v160
	v_fmac_f32_e32 v211, 0x3e0293ee, v161
	v_add_f32_e32 v212, v157, v212
	v_exp_f32_e32 v161, v211
	v_add_f32_e32 v211, v158, v212
	v_add_f32_e32 v211, v159, v211
	v_add_f32_e32 v211, v160, v211
	v_add_f32_e32 v212, v161, v211
	v_mov_b32_e32 v213, v212
	v_cvt_pk_bf16_f32 v146, v146, v147
	v_cvt_pk_bf16_f32 v147, v148, v149
	v_cvt_pk_bf16_f32 v148, v150, v151
	v_cvt_pk_bf16_f32 v149, v152, v153
	v_cvt_pk_bf16_f32 v150, v154, v155
	v_cvt_pk_bf16_f32 v151, v156, v157
	v_cvt_pk_bf16_f32 v152, v158, v159
	v_cvt_pk_bf16_f32 v153, v160, v161
	s_nop 1
	v_permlane32_swap_b32_e32 v212, v213
	v_permlane32_swap_b32_e32 v146, v148
	v_permlane32_swap_b32_e32 v147, v149
	v_permlane32_swap_b32_e32 v150, v152
	v_permlane32_swap_b32_e32 v151, v153
	s_barrier
	s_setprio 1
	s_waitcnt lgkmcnt(0)
	v_mfma_f32_32x32x16_bf16 v[98:113], v[146:149], v[206:209], v[98:113]
	v_lshl_add_u64 v[206:207], s[8:9], 0, v[238:239]
	v_lshl_add_u64 v[154:155], v[206:207], 0, s[92:93]
	s_add_i32 m0, s28, 0x8000
	s_nop 0
	global_load_lds_dwordx4 v[154:155], off
	v_mfma_f32_32x32x16_bf16 v[98:113], v[150:153], v[202:205], v[98:113]
	ds_read_b64_tr_b16 v[154:155], v1 offset:33792
	ds_read_b64_tr_b16 v[156:157], v1 offset:37888
	ds_read_b64_tr_b16 v[158:159], v1 offset:41984
	ds_read_b64_tr_b16 v[160:161], v1 offset:46080
	s_mov_b64 s[4:5], 0xf0000
	v_mfma_f32_32x32x16_bf16 v[114:129], v[146:149], v[198:201], v[114:129]
	v_lshl_add_u64 v[198:199], v[206:207], 0, s[4:5]
	s_add_i32 m0, s28, 0xa000
	s_nop 0
	global_load_lds_dwordx4 v[198:199], off
	v_mfma_f32_32x32x16_bf16 v[114:129], v[150:153], v[194:197], v[114:129]
	ds_read_b64_tr_b16 v[194:195], v1 offset:34304
	ds_read_b64_tr_b16 v[196:197], v1 offset:38400
	ds_read_b64_tr_b16 v[198:199], v1 offset:42496
	ds_read_b64_tr_b16 v[200:201], v1 offset:46592
	s_waitcnt lgkmcnt(4)
	v_mfma_f32_32x32x16_bf16 v[66:81], v[146:149], v[154:157], v[66:81]
	v_lshl_add_u64 v[154:155], v[206:207], 0, s[94:95]
	s_add_i32 m0, s28, 0xc000
	s_nop 0
	global_load_lds_dwordx4 v[154:155], off
	v_mfma_f32_32x32x16_bf16 v[66:81], v[150:153], v[158:161], v[66:81]
	ds_read_b64_tr_b16 v[154:155], v1 offset:34816
	ds_read_b64_tr_b16 v[156:157], v1 offset:38912
	ds_read_b64_tr_b16 v[158:159], v1 offset:43008
	ds_read_b64_tr_b16 v[160:161], v1 offset:47104
	s_mov_b64 s[4:5], 0x150000
	s_waitcnt lgkmcnt(4)
	v_mfma_f32_32x32x16_bf16 v[82:97], v[146:149], v[194:197], v[82:97]
	v_lshl_add_u64 v[194:195], v[206:207], 0, s[4:5]
	s_add_i32 m0, s28, 0xe000
	s_nop 0
	global_load_lds_dwordx4 v[194:195], off
	v_mfma_f32_32x32x16_bf16 v[82:97], v[150:153], v[198:201], v[82:97]
	ds_read_b64_tr_b16 v[194:195], v1 offset:35328
	ds_read_b64_tr_b16 v[196:197], v1 offset:39424
	ds_read_b64_tr_b16 v[198:199], v1 offset:43520
	ds_read_b64_tr_b16 v[200:201], v1 offset:47616
	s_waitcnt lgkmcnt(4)
	v_mfma_f32_32x32x16_bf16 v[34:49], v[146:149], v[154:157], v[34:49]
	v_mfma_f32_32x32x16_bf16 v[34:49], v[150:153], v[158:161], v[34:49]
	ds_read_b64_tr_b16 v[154:155], v1 offset:35840
	ds_read_b64_tr_b16 v[156:157], v1 offset:39936
	ds_read_b64_tr_b16 v[158:159], v1 offset:44032
	ds_read_b64_tr_b16 v[160:161], v1 offset:48128
	s_waitcnt lgkmcnt(4)
	v_mfma_f32_32x32x16_bf16 v[50:65], v[146:149], v[194:197], v[50:65]
	v_mfma_f32_32x32x16_bf16 v[50:65], v[150:153], v[198:201], v[50:65]
	ds_read_b64_tr_b16 v[194:195], v1 offset:36352
	ds_read_b64_tr_b16 v[196:197], v1 offset:40448
	ds_read_b64_tr_b16 v[198:199], v1 offset:44544
	ds_read_b64_tr_b16 v[200:201], v1 offset:48640
	s_waitcnt lgkmcnt(4)
	v_mfma_f32_32x32x16_bf16 v[18:33], v[146:149], v[154:157], v[18:33]
	v_mfma_f32_32x32x16_bf16 v[18:33], v[150:153], v[158:161], v[18:33]
	s_waitcnt lgkmcnt(0)
	v_mfma_f32_32x32x16_bf16 v[2:17], v[146:149], v[194:197], v[2:17]
	v_mfma_f32_32x32x16_bf16 v[2:17], v[150:153], v[198:201], v[2:17]
	s_setprio 0
	s_barrier
; template <int D0, int S> __device__ __forceinline__ VG vload(ldsc_t vb) { VG g; g.l0 = vtr(vb + v_rd_off(D0, 2 * S, 0)); g.h0 = vtr(vb + v_rd_off(D0, 2 * S, 1)); g.l1 = vtr(vb + v_rd_off(D0, 2 * S + 1, 0)); g.h1 = vtr(vb + v_rd_off(D0, 2 * S + 1, 1)); return g; }
; __device__ __forceinline__ void softmax_sub(f32x16& p, float& m_reg, float& l_reg, bf16x8& pa0, bf16x8& pa1, f32x16 (&o)[8], float* al_l, int r32, int hi, int dj, const float* tab, float cL, float cR) {
;     ...
;   if (dj <= -159) cb = cL;
;   else if (dj >= 159) cb = cR;
;   else { cb = 0.f; const int ib = dj - r32 + 4 * hi + 128;
; #pragma unroll
;     for (int r = 0; r < 16; ++r) { const int i0 = ib + (r & 3) + 8 * (r >> 2); p[r] += tab[min(max(i0, 0), 256)]; } }
; __device__ __forceinline__ void attn_unit(const bf16* __restrict__ qkvb, int seq, int q0, int h, ldsp_t ldsb, float* wsc, const float* tab, float lam) {
;     ...
;       { VG g0 = vload<0, 1>(vp + bo), g1 = vload<1, 1>(vp + bo);
;         softmax_sub(p1, m_reg, l_reg, pa0, pa1, o, al_l, r32, hi, 64 * j + 32 - q0w, tab, cL, cR);
	ds_read_b64_tr_b16 v[154:155], v1 offset:49152
	ds_read_b64_tr_b16 v[156:157], v1 offset:53248
	ds_read_b64_tr_b16 v[152:153], v1 offset:53760
	ds_read_b64_tr_b16 v[150:151], v1 offset:49664
	ds_read_b64_tr_b16 v[158:159], v1 offset:57344
	ds_read_b64_tr_b16 v[160:161], v1 offset:61440
	ds_read_b64_tr_b16 v[148:149], v1 offset:61952
	ds_read_b64_tr_b16 v[146:147], v1 offset:57856
	s_add_i32 s4, s26, 32
	s_cmpk_lt_i32 s4, 0xff62
	s_cbranch_scc1 .LBB0_558
	s_cmpk_gt_i32 s4, 0x9e
	s_cbranch_scc1 .LBB0_559
	v_add_u32_e32 v194, s26, v245
	v_add_u32_e32 v194, 0xa0, v194
	v_mov_b32_e32 v195, 0x100
	v_med3_i32 v195, v194, 0, v195
	v_lshl_add_u32 v202, v195, 2, s20
	v_max_i32_e32 v195, -1, v194
	v_add_u32_e32 v195, 1, v195
	v_min_u32_e32 v195, 0x100, v195
	v_lshl_add_u32 v203, v195, 2, s20
	v_max_i32_e32 v195, -2, v194
	v_add_u32_e32 v195, 2, v195
	v_min_u32_e32 v195, 0x100, v195
	v_lshl_add_u32 v204, v195, 2, s20
	v_max_i32_e32 v195, -3, v194
	v_add_u32_e32 v195, 3, v195
	v_min_u32_e32 v195, 0x100, v195
	v_lshl_add_u32 v205, v195, 2, s20
	v_max_i32_e32 v195, -8, v194
	v_add_u32_e32 v195, 8, v195
	v_min_u32_e32 v195, 0x100, v195
	v_lshl_add_u32 v206, v195, 2, s20
	v_max_i32_e32 v195, -9, v194
	v_add_u32_e32 v195, 9, v195
	v_min_u32_e32 v195, 0x100, v195
	v_lshl_add_u32 v207, v195, 2, s20
	v_max_i32_e32 v195, -10, v194
	v_add_u32_e32 v195, 10, v195
	v_min_u32_e32 v195, 0x100, v195
	v_lshl_add_u32 v208, v195, 2, s20
	v_max_i32_e32 v195, -11, v194
	v_add_u32_e32 v195, 11, v195
	v_min_u32_e32 v195, 0x100, v195
	v_lshl_add_u32 v209, v195, 2, s20
	v_max_i32_e32 v195, -16, v194
	v_max_i32_e32 v196, 0xffffffef, v194
	v_max_i32_e32 v197, 0xffffffee, v194
	v_max_i32_e32 v198, 0xffffffed, v194
	v_max_i32_e32 v199, 0xffffffe8, v194
	v_max_i32_e32 v200, 0xffffffe7, v194
	v_max_i32_e32 v201, 0xffffffe6, v194
	v_add_u32_e32 v195, 16, v195
	v_add_u32_e32 v196, 17, v196
	v_add_u32_e32 v197, 18, v197
	v_add_u32_e32 v198, 19, v198
	v_add_u32_e32 v199, 24, v199
	v_add_u32_e32 v200, 25, v200
	v_add_u32_e32 v201, 26, v201
	v_max_i32_e32 v194, 0xffffffe5, v194
	v_min_u32_e32 v195, 0x100, v195
	v_min_u32_e32 v196, 0x100, v196
	v_min_u32_e32 v197, 0x100, v197
	v_min_u32_e32 v198, 0x100, v198
	v_min_u32_e32 v199, 0x100, v199
	v_min_u32_e32 v200, 0x100, v200
	v_min_u32_e32 v201, 0x100, v201
	v_add_u32_e32 v194, 27, v194
	v_lshl_add_u32 v195, v195, 2, s20
	v_lshl_add_u32 v196, v196, 2, s20
	v_lshl_add_u32 v197, v197, 2, s20
	v_lshl_add_u32 v198, v198, 2, s20
	v_lshl_add_u32 v199, v199, 2, s20
	v_lshl_add_u32 v200, v200, 2, s20
	v_lshl_add_u32 v201, v201, 2, s20
	v_min_u32_e32 v194, 0x100, v194
	v_lshl_add_u32 v211, v194, 2, s20
	ds_read_b32 v194, v195
	ds_read_b32 v195, v196
	ds_read_b32 v196, v197
	ds_read_b32 v197, v198
	ds_read_b32 v198, v199
	ds_read_b32 v199, v200
	ds_read_b32 v200, v201
	ds_read_b32 v201, v211
	ds_read_b32 v202, v202
	ds_read_b32 v203, v203
	ds_read_b32 v204, v204
	ds_read_b32 v205, v205
	ds_read_b32 v206, v206
	ds_read_b32 v207, v207
	ds_read_b32 v208, v208
	ds_read_b32 v209, v209
	s_waitcnt lgkmcnt(0)
	v_pk_add_f32 v[144:145], v[144:145], v[200:201]
	v_pk_add_f32 v[142:143], v[142:143], v[198:199]
	v_pk_add_f32 v[140:141], v[140:141], v[196:197]
	v_pk_add_f32 v[138:139], v[138:139], v[194:195]
	v_pk_add_f32 v[136:137], v[136:137], v[208:209]
	v_pk_add_f32 v[134:135], v[134:135], v[206:207]
	v_pk_add_f32 v[132:133], v[132:133], v[204:205]
	v_pk_add_f32 v[130:131], v[130:131], v[202:203]
	s_mov_b32 s28, 0
	s_branch .LBB0_560

; #define SBAR() __builtin_amdgcn_sched_barrier(0)
; template <int D0, int S> __device__ __forceinline__ VG vload(ldsc_t vb) { VG g; g.l0 = vtr(vb + v_rd_off(D0, 2 * S, 0)); g.h0 = vtr(vb + v_rd_off(D0, 2 * S, 1)); g.l1 = vtr(vb + v_rd_off(D0, 2 * S + 1, 0)); g.h1 = vtr(vb + v_rd_off(D0, 2 * S + 1, 1)); return g; }
; __device__ __forceinline__ void softmax_sub(f32x16& p, float& m_reg, float& l_reg, bf16x8& pa0, bf16x8& pa1, f32x16 (&o)[8], float* al_l, int r32, int hi, int dj, const float* tab, float cL, float cR) {
;     ...
;   const float mnC = (cb - mn) * C;
;   float ps = 0;
; #pragma unroll
;   for (int r = 0; r < 16; ++r) { p[r] = __builtin_amdgcn_exp2f(fmaf(p[r], C, mnC)); ps += p[r]; }
;   { auto rr = __builtin_amdgcn_permlane32_swap(__float_as_uint(ps), __float_as_uint(ps), false, false);
;     ps = __uint_as_float(rr[0]) + __uint_as_float(rr[1]); }
;   l_reg = l_reg * alpha + ps;
;     ...
;   PK4(p, 0, pa0); PK4(p, 8, pa1);
;     ...
; }
; template <int S, class Dma> __device__ __forceinline__ void pv_run(f32x16 (&o)[8], ldsc_t vb, VG g0, VG g1, bf16x8 pa0, bf16x8 pa1, const Dma& dma) {
;   SBAR(); __builtin_amdgcn_s_setprio(1);
;   vmma(o[0], g0, pa0, pa1); dma(0); SBAR(); g0 = vload<2, S>(vb); SBAR();
;   vmma(o[1], g1, pa0, pa1); dma(1); SBAR(); g1 = vload<3, S>(vb); SBAR();
;   vmma(o[2], g0, pa0, pa1); dma(2); SBAR(); g0 = vload<4, S>(vb); SBAR();
;   vmma(o[3], g1, pa0, pa1); dma(3); SBAR(); g1 = vload<5, S>(vb); SBAR();
;   vmma(o[4], g0, pa0, pa1); dma(4); SBAR(); g0 = vload<6, S>(vb); SBAR();
;   vmma(o[5], g1, pa0, pa1); dma(5); SBAR(); g1 = vload<7, S>(vb); SBAR();
;   vmma(o[6], g0, pa0, pa1); dma(6); SBAR(); vmma(o[7], g1, pa0, pa1); dma(7); __builtin_amdgcn_s_setprio(0); SBAR();
.LBB0_562:
	v_sub_f32_e32 v195, s28, v211
	v_mul_f32_e32 v195, 0x3e0293ee, v195
	v_fmamk_f32 v130, v130, 0x3e0293ee, v195
	v_exp_f32_e32 v130, v130
	v_fmamk_f32 v131, v131, 0x3e0293ee, v195
	v_exp_f32_e32 v131, v131
	v_fmamk_f32 v132, v132, 0x3e0293ee, v195
	v_exp_f32_e32 v132, v132
	v_fmamk_f32 v133, v133, 0x3e0293ee, v195
	v_exp_f32_e32 v133, v133
	v_fmamk_f32 v134, v134, 0x3e0293ee, v195
	v_add_f32_e32 v196, 0, v130
	v_exp_f32_e32 v134, v134
	v_fmamk_f32 v135, v135, 0x3e0293ee, v195
	v_add_f32_e32 v196, v131, v196
	v_exp_f32_e32 v135, v135
	v_fmamk_f32 v136, v136, 0x3e0293ee, v195
	v_add_f32_e32 v196, v132, v196
	v_exp_f32_e32 v136, v136
	v_fmamk_f32 v137, v137, 0x3e0293ee, v195
	v_add_f32_e32 v196, v133, v196
	v_exp_f32_e32 v137, v137
	v_fmamk_f32 v138, v138, 0x3e0293ee, v195
	v_add_f32_e32 v196, v134, v196
	v_exp_f32_e32 v138, v138
	v_fmamk_f32 v139, v139, 0x3e0293ee, v195
	v_add_f32_e32 v196, v135, v196
	v_exp_f32_e32 v139, v139
	v_fmamk_f32 v140, v140, 0x3e0293ee, v195
	v_add_f32_e32 v196, v136, v196
	v_exp_f32_e32 v140, v140
	v_fmamk_f32 v141, v141, 0x3e0293ee, v195
	v_add_f32_e32 v196, v137, v196
	v_exp_f32_e32 v141, v141
	v_fmamk_f32 v142, v142, 0x3e0293ee, v195
	v_add_f32_e32 v196, v138, v196
	v_exp_f32_e32 v142, v142
	v_fmamk_f32 v143, v143, 0x3e0293ee, v195
	v_add_f32_e32 v196, v139, v196
	v_exp_f32_e32 v143, v143
	v_fmamk_f32 v144, v144, 0x3e0293ee, v195
	v_add_f32_e32 v196, v140, v196
	v_exp_f32_e32 v144, v144
	v_fmac_f32_e32 v195, 0x3e0293ee, v145
	v_add_f32_e32 v196, v141, v196
	v_exp_f32_e32 v145, v195
	v_add_f32_e32 v195, v142, v196
	v_add_f32_e32 v195, v143, v195
	v_add_f32_e32 v195, v144, v195
	v_add_f32_e32 v195, v145, v195
	v_mov_b32_e32 v196, v195
	v_add_f32_e32 v194, v212, v213
	s_nop 0
	v_permlane32_swap_b32_e32 v195, v196
	v_fmac_f32_e32 v194, v249, v243
	v_add_f32_e32 v249, v195, v196
	s_add_i32 s25, s25, 1
	v_fmac_f32_e32 v249, v194, v214
	v_cvt_pk_bf16_f32 v130, v130, v131
	v_cvt_pk_bf16_f32 v131, v132, v133
	v_cvt_pk_bf16_f32 v132, v134, v135
	v_cvt_pk_bf16_f32 v133, v136, v137
	v_cvt_pk_bf16_f32 v134, v138, v139
	v_cvt_pk_bf16_f32 v135, v140, v141
	v_cvt_pk_bf16_f32 v136, v142, v143
	v_cvt_pk_bf16_f32 v137, v144, v145
	s_nop 0
	v_permlane32_swap_b32_e32 v130, v132
	v_permlane32_swap_b32_e32 v131, v133
	v_permlane32_swap_b32_e32 v134, v136
	v_permlane32_swap_b32_e32 v135, v137
	s_waitcnt vmcnt(4)
	s_barrier
	s_setprio 1
	s_waitcnt lgkmcnt(0)
	v_mfma_f32_32x32x16_bf16 v[98:113], v[130:133], v[154:157], v[98:113]
	v_mfma_f32_32x32x16_bf16 v[98:113], v[134:137], v[158:161], v[98:113]
	ds_read_b64_tr_b16 v[138:139], v1 offset:50176
	ds_read_b64_tr_b16 v[140:141], v1 offset:54272
	ds_read_b64_tr_b16 v[142:143], v1 offset:58368
	ds_read_b64_tr_b16 v[144:145], v1 offset:62464
	v_mfma_f32_32x32x16_bf16 v[114:129], v[130:133], v[150:153], v[114:129]
	v_mfma_f32_32x32x16_bf16 v[114:129], v[134:137], v[146:149], v[114:129]
	ds_read_b64_tr_b16 v[146:147], v1 offset:50688
	ds_read_b64_tr_b16 v[148:149], v1 offset:54784
	ds_read_b64_tr_b16 v[150:151], v1 offset:58880
	ds_read_b64_tr_b16 v[152:153], v1 offset:62976
	s_waitcnt lgkmcnt(4)
	v_mfma_f32_32x32x16_bf16 v[66:81], v[130:133], v[138:141], v[66:81]
	v_mfma_f32_32x32x16_bf16 v[66:81], v[134:137], v[142:145], v[66:81]
	ds_read_b64_tr_b16 v[138:139], v1 offset:51200
	ds_read_b64_tr_b16 v[140:141], v1 offset:55296
	ds_read_b64_tr_b16 v[142:143], v1 offset:59392
	ds_read_b64_tr_b16 v[144:145], v1 offset:63488
	s_waitcnt lgkmcnt(4)
	v_mfma_f32_32x32x16_bf16 v[82:97], v[130:133], v[146:149], v[82:97]
	v_mfma_f32_32x32x16_bf16 v[82:97], v[134:137], v[150:153], v[82:97]
	ds_read_b64_tr_b16 v[146:147], v1 offset:51712
	ds_read_b64_tr_b16 v[148:149], v1 offset:55808
	ds_read_b64_tr_b16 v[150:151], v1 offset:59904
	ds_read_b64_tr_b16 v[152:153], v1 offset:64000
	s_waitcnt lgkmcnt(4)
	v_mfma_f32_32x32x16_bf16 v[34:49], v[130:133], v[138:141], v[34:49]
	v_mfma_f32_32x32x16_bf16 v[34:49], v[134:137], v[142:145], v[34:49]
	ds_read_b64_tr_b16 v[138:139], v1 offset:52224
	ds_read_b64_tr_b16 v[140:141], v1 offset:56320
	ds_read_b64_tr_b16 v[142:143], v1 offset:60416
	ds_read_b64_tr_b16 v[144:145], v1 offset:64512
	s_waitcnt lgkmcnt(4)
	v_mfma_f32_32x32x16_bf16 v[50:65], v[130:133], v[146:149], v[50:65]
	v_mfma_f32_32x32x16_bf16 v[50:65], v[134:137], v[150:153], v[50:65]
	ds_read_b64_tr_b16 v[146:147], v1 offset:52736
	ds_read_b64_tr_b16 v[148:149], v1 offset:56832
	ds_read_b64_tr_b16 v[150:151], v1 offset:60928
	ds_read_b64_tr_b16 v[152:153], v1 offset:65024
	s_waitcnt lgkmcnt(4)
	v_mfma_f32_32x32x16_bf16 v[18:33], v[130:133], v[138:141], v[18:33]
	v_mfma_f32_32x32x16_bf16 v[18:33], v[134:137], v[142:145], v[18:33]
	s_waitcnt lgkmcnt(0)
	v_mfma_f32_32x32x16_bf16 v[2:17], v[130:133], v[146:149], v[2:17]
	v_mfma_f32_32x32x16_bf16 v[2:17], v[134:137], v[150:153], v[2:17]
	s_setprio 0
	s_add_i32 s26, s26, 64
	s_add_i32 s27, s27, 0x10000
	s_add_u32 s8, s8, 0xc0000
	s_addc_u32 s9, s9, 0
	s_cmp_eq_u32 s11, s25
	s_cbranch_scc0 .LBB0_548
	s_branch .LBB0_569

; #define SBAR() __builtin_amdgcn_sched_barrier(0)
; #define KF(a, o) (*(const __attribute__((address_space(3))) bf16x8*)((a) + (o)))
; template <class Hook> __device__ __forceinline__ void qk_sub(f32x16& p, ldsc_t k0, ldsc_t k1, ldsc_t k2, ldsc_t k3, int kd, const bf16x8* qr, const Hook& hook) {
;     ...
;   SBAR();
;   bf16x8 f0 = KF(k0, 0), f1 = KF(k1, 0), f2 = KF(k2, 0), f3 = KF(k3, 0); SBAR(); __builtin_amdgcn_s_setprio(1);
;   p = __builtin_amdgcn_mfma_f32_32x32x16_bf16(f0, qr[0], f32x16{}, 0, 0, 0); f0 = KF(k0 + kd, 0); SBAR();
;   p = __builtin_amdgcn_mfma_f32_32x32x16_bf16(f1, qr[1], p, 0, 0, 0); f1 = KF(k1 + kd, 0); hook(0); SBAR();
;   p = __builtin_amdgcn_mfma_f32_32x32x16_bf16(f2, qr[2], p, 0, 0, 0); f2 = KF(k2 + kd, 0); SBAR();
;   p = __builtin_amdgcn_mfma_f32_32x32x16_bf16(f3, qr[3], p, 0, 0, 0); f3 = KF(k3 + kd, 0); hook(1); SBAR();
;   p = __builtin_amdgcn_mfma_f32_32x32x16_bf16(f0, qr[4], p, 0, 0, 0); SBAR();
;   p = __builtin_amdgcn_mfma_f32_32x32x16_bf16(f1, qr[5], p, 0, 0, 0); hook(2); SBAR();
;   p = __builtin_amdgcn_mfma_f32_32x32x16_bf16(f2, qr[6], p, 0, 0, 0); SBAR();
;   p = __builtin_amdgcn_mfma_f32_32x32x16_bf16(f3, qr[7], p, 0, 0, 0); hook(3); __builtin_amdgcn_s_setprio(0); SBAR();
; __device__ __forceinline__ void softmax_sub(f32x16& p, float& m_reg, float& l_reg, bf16x8& pa0, bf16x8& pa1, f32x16 (&o)[8], float* al_l, int r32, int hi, int dj, const float* tab, float cL, float cR) {
;     ...
;   if (dj <= -159) cb = cL;
;   else if (dj >= 159) cb = cR;
;   else { cb = 0.f; const int ib = dj - r32 + 4 * hi + 128;
; #pragma unroll
;     for (int r = 0; r < 16; ++r) { const int i0 = ib + (r & 3) + 8 * (r >> 2); p[r] += tab[min(max(i0, 0), 256)]; } }
.LBB0_569:
	s_waitcnt vmcnt(0)
	s_barrier
	v_add_u32_e32 v195, 0x80, v245
	v_add_u32_e32 v1, s24, v252
	v_add_u32_e32 v194, s24, v253
	v_add_u32_e32 v200, s24, v241
	v_add_u32_e32 v204, s24, v244
	ds_read_b128 v[130:133], v1
	ds_read_b128 v[134:137], v194
	ds_read_b128 v[138:141], v200
	ds_read_b128 v[142:145], v204
	s_setprio 1
	s_waitcnt lgkmcnt(3)
	v_mfma_f32_32x32x16_bf16 v[146:161], v[130:133], v[190:193], 0
	v_add_u32_e32 v208, v1, v251
	ds_read_b128 v[130:133], v208
	s_waitcnt lgkmcnt(3)
	v_mfma_f32_32x32x16_bf16 v[146:161], v[134:137], v[186:189], v[146:161]
	v_add_u32_e32 v209, v194, v251
	ds_read_b128 v[134:137], v209
	s_waitcnt lgkmcnt(3)
	v_mfma_f32_32x32x16_bf16 v[146:161], v[138:141], v[182:185], v[146:161]
	v_add_u32_e32 v210, v200, v251
	ds_read_b128 v[138:141], v210
	s_waitcnt lgkmcnt(3)
	v_mfma_f32_32x32x16_bf16 v[146:161], v[142:145], v[178:181], v[146:161]
	v_add_u32_e32 v212, v204, v251
	ds_read_b128 v[142:145], v212
	s_waitcnt lgkmcnt(3)
	v_mfma_f32_32x32x16_bf16 v[146:161], v[130:133], v[174:177], v[146:161]
	s_waitcnt lgkmcnt(2)
	v_mfma_f32_32x32x16_bf16 v[146:161], v[134:137], v[170:173], v[146:161]
	s_waitcnt lgkmcnt(1)
	v_mfma_f32_32x32x16_bf16 v[146:161], v[138:141], v[166:169], v[146:161]
	s_waitcnt lgkmcnt(0)
	v_mfma_f32_32x32x16_bf16 v[146:161], v[142:145], v[162:165], v[146:161]
	s_setprio 0
	ds_read_b128 v[130:133], v1 offset:8192
	ds_read_b128 v[196:199], v194 offset:8192
	ds_read_b128 v[200:203], v200 offset:8192
	ds_read_b128 v[204:207], v204 offset:8192
	s_setprio 1
	s_waitcnt lgkmcnt(3)
	v_mfma_f32_32x32x16_bf16 v[130:145], v[130:133], v[190:193], 0
	ds_read_b128 v[190:193], v208 offset:8192
	s_waitcnt lgkmcnt(3)
	v_mfma_f32_32x32x16_bf16 v[130:145], v[196:199], v[186:189], v[130:145]
	ds_read_b128 v[186:189], v209 offset:8192
	s_waitcnt lgkmcnt(3)
	v_mfma_f32_32x32x16_bf16 v[130:145], v[200:203], v[182:185], v[130:145]
	ds_read_b128 v[182:185], v210 offset:8192
	s_waitcnt lgkmcnt(3)
	v_mfma_f32_32x32x16_bf16 v[130:145], v[204:207], v[178:181], v[130:145]
	ds_read_b128 v[178:181], v212 offset:8192
	s_waitcnt lgkmcnt(3)
	v_mfma_f32_32x32x16_bf16 v[130:145], v[190:193], v[174:177], v[130:145]
	s_waitcnt lgkmcnt(2)
	v_mfma_f32_32x32x16_bf16 v[130:145], v[186:189], v[170:173], v[130:145]
	s_waitcnt lgkmcnt(1)
	v_mfma_f32_32x32x16_bf16 v[130:145], v[182:185], v[166:169], v[130:145]
	s_waitcnt lgkmcnt(0)
	v_mfma_f32_32x32x16_bf16 v[130:145], v[178:181], v[162:165], v[130:145]
	s_setprio 0
	s_barrier
	v_add_u32_e32 v1, s24, v250
	ds_read_b64_tr_b16 v[170:171], v1 offset:32768
	ds_read_b64_tr_b16 v[172:173], v1 offset:36864
	ds_read_b64_tr_b16 v[168:169], v1 offset:37376
	ds_read_b64_tr_b16 v[166:167], v1 offset:33280
	ds_read_b64_tr_b16 v[174:175], v1 offset:40960
	ds_read_b64_tr_b16 v[176:177], v1 offset:45056
	ds_read_b64_tr_b16 v[164:165], v1 offset:45568
	ds_read_b64_tr_b16 v[162:163], v1 offset:41472
	s_lshl_b32 s8, s11, 6
	s_sub_i32 s4, s8, s21
	s_cmpk_lt_i32 s4, 0xff62
	s_cbranch_scc1 .LBB0_572
	s_cmpk_gt_i32 s4, 0x9e
	v_mov_b32_e32 v244, v240
	v_mov_b32_e32 v245, v0
	v_mov_b64_e32 v[250:251], 0x200
	v_mov_b64_e32 v[252:253], 0x1ff
	s_cbranch_scc1 .LBB0_573
	v_add_u32_e32 v178, s4, v195
	v_mov_b32_e32 v0, 0x100
	v_med3_i32 v179, v178, 0, v0
	v_lshl_add_u32 v186, v179, 2, s20
	v_max_i32_e32 v179, -1, v178
	v_add_u32_e32 v179, 1, v179
	v_min_u32_e32 v179, 0x100, v179
	v_lshl_add_u32 v187, v179, 2, s20
	v_max_i32_e32 v179, -2, v178
	v_add_u32_e32 v179, 2, v179
	v_min_u32_e32 v179, 0x100, v179
	v_lshl_add_u32 v188, v179, 2, s20
	v_max_i32_e32 v179, -3, v178
	v_add_u32_e32 v179, 3, v179
	v_min_u32_e32 v179, 0x100, v179
	v_lshl_add_u32 v189, v179, 2, s20
	v_max_i32_e32 v179, -8, v178
	v_add_u32_e32 v179, 8, v179
	v_min_u32_e32 v179, 0x100, v179
	v_lshl_add_u32 v190, v179, 2, s20
	v_max_i32_e32 v179, -9, v178
	v_add_u32_e32 v179, 9, v179
	v_min_u32_e32 v179, 0x100, v179
	v_lshl_add_u32 v191, v179, 2, s20
	v_max_i32_e32 v179, -10, v178
	v_add_u32_e32 v179, 10, v179
	v_min_u32_e32 v179, 0x100, v179
	v_lshl_add_u32 v192, v179, 2, s20
	v_max_i32_e32 v179, -11, v178
	v_add_u32_e32 v179, 11, v179
	v_min_u32_e32 v179, 0x100, v179
	v_lshl_add_u32 v193, v179, 2, s20
	v_max_i32_e32 v179, -16, v178
	v_max_i32_e32 v180, 0xffffffef, v178
	v_max_i32_e32 v181, 0xffffffee, v178
	v_max_i32_e32 v182, 0xffffffed, v178
	v_max_i32_e32 v183, 0xffffffe8, v178
	v_max_i32_e32 v184, 0xffffffe7, v178
	v_max_i32_e32 v185, 0xffffffe6, v178
	v_add_u32_e32 v179, 16, v179
	v_add_u32_e32 v180, 17, v180
	v_add_u32_e32 v181, 18, v181
	v_add_u32_e32 v182, 19, v182
	v_add_u32_e32 v183, 24, v183
	v_add_u32_e32 v184, 25, v184
	v_add_u32_e32 v185, 26, v185
	v_max_i32_e32 v178, 0xffffffe5, v178
	v_min_u32_e32 v179, 0x100, v179
	v_min_u32_e32 v180, 0x100, v180
	v_min_u32_e32 v181, 0x100, v181
	v_min_u32_e32 v182, 0x100, v182
	v_min_u32_e32 v183, 0x100, v183
	v_min_u32_e32 v184, 0x100, v184
	v_min_u32_e32 v185, 0x100, v185
	v_add_u32_e32 v178, 27, v178
	v_lshl_add_u32 v179, v179, 2, s20
	v_lshl_add_u32 v180, v180, 2, s20
	v_lshl_add_u32 v181, v181, 2, s20
	v_lshl_add_u32 v182, v182, 2, s20
	v_lshl_add_u32 v183, v183, 2, s20
	v_lshl_add_u32 v184, v184, 2, s20
	v_lshl_add_u32 v185, v185, 2, s20
	v_min_u32_e32 v178, 0x100, v178
	v_lshl_add_u32 v194, v178, 2, s20
	ds_read_b32 v178, v179
	ds_read_b32 v179, v180
	ds_read_b32 v180, v181
	ds_read_b32 v181, v182
	ds_read_b32 v182, v183
	ds_read_b32 v183, v184
	ds_read_b32 v184, v185
	ds_read_b32 v185, v194
	ds_read_b32 v186, v186
	ds_read_b32 v187, v187
	ds_read_b32 v188, v188
	ds_read_b32 v189, v189
	ds_read_b32 v190, v190
	ds_read_b32 v191, v191
	ds_read_b32 v192, v192
	ds_read_b32 v193, v193
	s_waitcnt lgkmcnt(0)
	v_pk_add_f32 v[160:161], v[160:161], v[184:185]
	v_pk_add_f32 v[158:159], v[158:159], v[182:183]
	v_pk_add_f32 v[156:157], v[156:157], v[180:181]
	v_pk_add_f32 v[154:155], v[154:155], v[178:179]
	v_pk_add_f32 v[152:153], v[152:153], v[192:193]
	v_pk_add_f32 v[150:151], v[150:151], v[190:191]
	v_pk_add_f32 v[148:149], v[148:149], v[188:189]
	v_pk_add_f32 v[146:147], v[146:147], v[186:187]
	s_mov_b32 s9, 0
	v_mov_b32_e32 v246, 0x260
	s_branch .LBB0_574

; #define SBAR() __builtin_amdgcn_sched_barrier(0)
; template <int D0, int S> __device__ __forceinline__ VG vload(ldsc_t vb) { VG g; g.l0 = vtr(vb + v_rd_off(D0, 2 * S, 0)); g.h0 = vtr(vb + v_rd_off(D0, 2 * S, 1)); g.l1 = vtr(vb + v_rd_off(D0, 2 * S + 1, 0)); g.h1 = vtr(vb + v_rd_off(D0, 2 * S + 1, 1)); return g; }
; __device__ __forceinline__ void softmax_sub(f32x16& p, float& m_reg, float& l_reg, bf16x8& pa0, bf16x8& pa1, f32x16 (&o)[8], float* al_l, int r32, int hi, int dj, const float* tab, float cL, float cR) {
;     ...
;   const float mnC = (cb - mn) * C;
;   float ps = 0;
; #pragma unroll
;   for (int r = 0; r < 16; ++r) { p[r] = __builtin_amdgcn_exp2f(fmaf(p[r], C, mnC)); ps += p[r]; }
;   { auto rr = __builtin_amdgcn_permlane32_swap(__float_as_uint(ps), __float_as_uint(ps), false, false);
;     ps = __uint_as_float(rr[0]) + __uint_as_float(rr[1]); }
;   l_reg = l_reg * alpha + ps;
;     ...
;   PK4(p, 0, pa0); PK4(p, 8, pa1);
;     ...
; }
; template <int S, class Dma> __device__ __forceinline__ void pv_run(f32x16 (&o)[8], ldsc_t vb, VG g0, VG g1, bf16x8 pa0, bf16x8 pa1, const Dma& dma) {
;   SBAR(); __builtin_amdgcn_s_setprio(1);
;   vmma(o[0], g0, pa0, pa1); dma(0); SBAR(); g0 = vload<2, S>(vb); SBAR();
;   vmma(o[1], g1, pa0, pa1); dma(1); SBAR(); g1 = vload<3, S>(vb); SBAR();
;   vmma(o[2], g0, pa0, pa1); dma(2); SBAR(); g0 = vload<4, S>(vb); SBAR();
;   vmma(o[3], g1, pa0, pa1); dma(3); SBAR(); g1 = vload<5, S>(vb); SBAR();
;   vmma(o[4], g0, pa0, pa1); dma(4); SBAR(); g0 = vload<6, S>(vb); SBAR();
;   vmma(o[5], g1, pa0, pa1); dma(5); SBAR(); g1 = vload<7, S>(vb); SBAR();
;   vmma(o[6], g0, pa0, pa1); dma(6); SBAR(); vmma(o[7], g1, pa0, pa1); dma(7); __builtin_amdgcn_s_setprio(0); SBAR();
.LBB0_576:
	v_sub_f32_e32 v178, s9, v196
	v_mul_f32_e32 v178, 0x3e0293ee, v178
	v_fmamk_f32 v146, v146, 0x3e0293ee, v178
	v_exp_f32_e32 v146, v146
	v_fmamk_f32 v147, v147, 0x3e0293ee, v178
	v_exp_f32_e32 v147, v147
	v_fmamk_f32 v148, v148, 0x3e0293ee, v178
	v_exp_f32_e32 v148, v148
	v_fmamk_f32 v149, v149, 0x3e0293ee, v178
	v_exp_f32_e32 v149, v149
	v_fmamk_f32 v150, v150, 0x3e0293ee, v178
	v_add_f32_e32 v179, 0, v146
	v_exp_f32_e32 v150, v150
	v_fmamk_f32 v151, v151, 0x3e0293ee, v178
	v_add_f32_e32 v179, v147, v179
	v_exp_f32_e32 v151, v151
	v_fmamk_f32 v152, v152, 0x3e0293ee, v178
	v_add_f32_e32 v179, v148, v179
	v_exp_f32_e32 v152, v152
	v_fmamk_f32 v153, v153, 0x3e0293ee, v178
	v_add_f32_e32 v179, v149, v179
	v_exp_f32_e32 v153, v153
	v_fmamk_f32 v154, v154, 0x3e0293ee, v178
	v_add_f32_e32 v179, v150, v179
	v_exp_f32_e32 v154, v154
	v_fmamk_f32 v155, v155, 0x3e0293ee, v178
	v_add_f32_e32 v179, v151, v179
	v_exp_f32_e32 v155, v155
	v_fmamk_f32 v156, v156, 0x3e0293ee, v178
	v_add_f32_e32 v179, v152, v179
	v_exp_f32_e32 v156, v156
	v_fmamk_f32 v157, v157, 0x3e0293ee, v178
	v_add_f32_e32 v179, v153, v179
	v_exp_f32_e32 v157, v157
	v_fmamk_f32 v158, v158, 0x3e0293ee, v178
	v_add_f32_e32 v179, v154, v179
	v_exp_f32_e32 v158, v158
	v_fmamk_f32 v159, v159, 0x3e0293ee, v178
	v_add_f32_e32 v179, v155, v179
	v_exp_f32_e32 v159, v159
	v_fmamk_f32 v160, v160, 0x3e0293ee, v178
	v_add_f32_e32 v179, v156, v179
	v_exp_f32_e32 v160, v160
	v_fmac_f32_e32 v178, 0x3e0293ee, v161
	v_add_f32_e32 v179, v157, v179
	v_exp_f32_e32 v161, v178
	v_add_f32_e32 v178, v158, v179
	v_add_f32_e32 v178, v159, v178
	v_add_f32_e32 v178, v160, v178
	v_add_f32_e32 v178, v161, v178
	v_mov_b32_e32 v179, v178
	v_cvt_pk_bf16_f32 v146, v146, v147
	v_cvt_pk_bf16_f32 v147, v148, v149
	v_cvt_pk_bf16_f32 v148, v150, v151
	v_cvt_pk_bf16_f32 v149, v152, v153
	v_cvt_pk_bf16_f32 v150, v154, v155
	v_cvt_pk_bf16_f32 v151, v156, v157
	v_cvt_pk_bf16_f32 v152, v158, v159
	v_cvt_pk_bf16_f32 v153, v160, v161
	s_nop 1
	v_permlane32_swap_b32_e32 v178, v179
	v_permlane32_swap_b32_e32 v146, v148
	v_permlane32_swap_b32_e32 v147, v149
	v_permlane32_swap_b32_e32 v150, v152
	v_permlane32_swap_b32_e32 v151, v153
	s_barrier
	s_setprio 1
	s_waitcnt lgkmcnt(0)
	v_mfma_f32_32x32x16_bf16 v[98:113], v[146:149], v[170:173], v[98:113]
	v_mfma_f32_32x32x16_bf16 v[98:113], v[150:153], v[174:177], v[98:113]
	ds_read_b64_tr_b16 v[154:155], v1 offset:33792
	ds_read_b64_tr_b16 v[156:157], v1 offset:37888
	ds_read_b64_tr_b16 v[158:159], v1 offset:41984
	ds_read_b64_tr_b16 v[160:161], v1 offset:46080
	v_mfma_f32_32x32x16_bf16 v[114:129], v[146:149], v[166:169], v[114:129]
	v_mfma_f32_32x32x16_bf16 v[114:129], v[150:153], v[162:165], v[114:129]
	ds_read_b64_tr_b16 v[162:163], v1 offset:34304
	ds_read_b64_tr_b16 v[164:165], v1 offset:38400
	ds_read_b64_tr_b16 v[166:167], v1 offset:42496
	ds_read_b64_tr_b16 v[168:169], v1 offset:46592
	s_waitcnt lgkmcnt(4)
	v_mfma_f32_32x32x16_bf16 v[66:81], v[146:149], v[154:157], v[66:81]
	v_mfma_f32_32x32x16_bf16 v[66:81], v[150:153], v[158:161], v[66:81]
	ds_read_b64_tr_b16 v[154:155], v1 offset:34816
	ds_read_b64_tr_b16 v[156:157], v1 offset:38912
	ds_read_b64_tr_b16 v[158:159], v1 offset:43008
	ds_read_b64_tr_b16 v[160:161], v1 offset:47104
	s_waitcnt lgkmcnt(4)
	v_mfma_f32_32x32x16_bf16 v[82:97], v[146:149], v[162:165], v[82:97]
	v_mfma_f32_32x32x16_bf16 v[82:97], v[150:153], v[166:169], v[82:97]
	ds_read_b64_tr_b16 v[162:163], v1 offset:35328
	ds_read_b64_tr_b16 v[164:165], v1 offset:39424
	ds_read_b64_tr_b16 v[166:167], v1 offset:43520
	ds_read_b64_tr_b16 v[168:169], v1 offset:47616
	s_waitcnt lgkmcnt(4)
	v_mfma_f32_32x32x16_bf16 v[34:49], v[146:149], v[154:157], v[34:49]
	v_mfma_f32_32x32x16_bf16 v[34:49], v[150:153], v[158:161], v[34:49]
	ds_read_b64_tr_b16 v[154:155], v1 offset:35840
	ds_read_b64_tr_b16 v[156:157], v1 offset:39936
	ds_read_b64_tr_b16 v[158:159], v1 offset:44032
	ds_read_b64_tr_b16 v[160:161], v1 offset:48128
	s_waitcnt lgkmcnt(4)
	v_mfma_f32_32x32x16_bf16 v[50:65], v[146:149], v[162:165], v[50:65]
	v_mfma_f32_32x32x16_bf16 v[50:65], v[150:153], v[166:169], v[50:65]
	ds_read_b64_tr_b16 v[162:163], v1 offset:36352
	ds_read_b64_tr_b16 v[164:165], v1 offset:40448
	ds_read_b64_tr_b16 v[166:167], v1 offset:44544
	ds_read_b64_tr_b16 v[168:169], v1 offset:48640
	s_waitcnt lgkmcnt(4)
	v_mfma_f32_32x32x16_bf16 v[18:33], v[146:149], v[154:157], v[18:33]
	v_mfma_f32_32x32x16_bf16 v[18:33], v[150:153], v[158:161], v[18:33]
	s_waitcnt lgkmcnt(0)
	v_mfma_f32_32x32x16_bf16 v[2:17], v[146:149], v[162:165], v[2:17]
	v_mfma_f32_32x32x16_bf16 v[2:17], v[150:153], v[166:169], v[2:17]
	s_setprio 0
	s_barrier
; template <int D0, int S> __device__ __forceinline__ VG vload(ldsc_t vb) { VG g; g.l0 = vtr(vb + v_rd_off(D0, 2 * S, 0)); g.h0 = vtr(vb + v_rd_off(D0, 2 * S, 1)); g.l1 = vtr(vb + v_rd_off(D0, 2 * S + 1, 0)); g.h1 = vtr(vb + v_rd_off(D0, 2 * S + 1, 1)); return g; }
; __device__ __forceinline__ void softmax_sub(f32x16& p, float& m_reg, float& l_reg, bf16x8& pa0, bf16x8& pa1, f32x16 (&o)[8], float* al_l, int r32, int hi, int dj, const float* tab, float cL, float cR) {
;     ...
;   if (dj <= -159) cb = cL;
;   else if (dj >= 159) cb = cR;
;   else { cb = 0.f; const int ib = dj - r32 + 4 * hi + 128;
; #pragma unroll
;     for (int r = 0; r < 16; ++r) { const int i0 = ib + (r & 3) + 8 * (r >> 2); p[r] += tab[min(max(i0, 0), 256)]; } }
; __device__ __forceinline__ void attn_unit(const bf16* __restrict__ qkvb, int seq, int q0, int h, ldsp_t ldsb, float* wsc, const float* tab, float lam) {
;     ...
;       { VG g0 = vload<0, 1>(vp + bo), g1 = vload<1, 1>(vp + bo);
;         softmax_sub(p1, m_reg, l_reg, pa0, pa1, o, al_l, r32, hi, 64 * j + 32 - q0w, tab, cL, cR);
	ds_read_b64_tr_b16 v[154:155], v1 offset:49152
	ds_read_b64_tr_b16 v[156:157], v1 offset:53248
	ds_read_b64_tr_b16 v[152:153], v1 offset:53760
	ds_read_b64_tr_b16 v[150:151], v1 offset:49664
	ds_read_b64_tr_b16 v[158:159], v1 offset:57344
	ds_read_b64_tr_b16 v[160:161], v1 offset:61440
	ds_read_b64_tr_b16 v[148:149], v1 offset:61952
	ds_read_b64_tr_b16 v[146:147], v1 offset:57856
	s_or_b32 s4, s8, 32
	s_sub_i32 s4, s4, s21
	s_cmpk_lt_i32 s4, 0xff62
	s_cbranch_scc1 .LBB0_580
	s_cmpk_gt_i32 s4, 0x9e
	s_cbranch_scc1 .LBB0_579
	v_add_u32_e32 v162, s4, v195
	v_mov_b32_e32 v0, 0x100
	v_med3_i32 v163, v162, 0, v0
	v_lshl_add_u32 v170, v163, 2, s20
	v_max_i32_e32 v163, -1, v162
	v_add_u32_e32 v163, 1, v163
	v_min_u32_e32 v163, 0x100, v163
	v_lshl_add_u32 v171, v163, 2, s20
	v_max_i32_e32 v163, -2, v162
	v_add_u32_e32 v163, 2, v163
	v_min_u32_e32 v163, 0x100, v163
	v_lshl_add_u32 v172, v163, 2, s20
	v_max_i32_e32 v163, -3, v162
	v_add_u32_e32 v163, 3, v163
	v_min_u32_e32 v163, 0x100, v163
	v_lshl_add_u32 v173, v163, 2, s20
	v_max_i32_e32 v163, -8, v162
	v_add_u32_e32 v163, 8, v163
	v_min_u32_e32 v163, 0x100, v163
	v_lshl_add_u32 v174, v163, 2, s20
	v_max_i32_e32 v163, -9, v162
	v_add_u32_e32 v163, 9, v163
	v_min_u32_e32 v163, 0x100, v163
	v_lshl_add_u32 v175, v163, 2, s20
	v_max_i32_e32 v163, -10, v162
	v_add_u32_e32 v163, 10, v163
	v_min_u32_e32 v163, 0x100, v163
	v_lshl_add_u32 v176, v163, 2, s20
	v_max_i32_e32 v163, -11, v162
	v_add_u32_e32 v163, 11, v163
	v_min_u32_e32 v163, 0x100, v163
	v_lshl_add_u32 v177, v163, 2, s20
	v_max_i32_e32 v163, -16, v162
	v_max_i32_e32 v164, 0xffffffef, v162
	v_max_i32_e32 v165, 0xffffffee, v162
	v_max_i32_e32 v166, 0xffffffed, v162
	v_max_i32_e32 v167, 0xffffffe8, v162
	v_max_i32_e32 v168, 0xffffffe7, v162
	v_max_i32_e32 v169, 0xffffffe6, v162
	v_add_u32_e32 v163, 16, v163
	v_add_u32_e32 v164, 17, v164
	v_add_u32_e32 v165, 18, v165
	v_add_u32_e32 v166, 19, v166
	v_add_u32_e32 v167, 24, v167
	v_add_u32_e32 v168, 25, v168
	v_add_u32_e32 v169, 26, v169
	v_max_i32_e32 v162, 0xffffffe5, v162
	v_min_u32_e32 v163, 0x100, v163
	v_min_u32_e32 v164, 0x100, v164
	v_min_u32_e32 v165, 0x100, v165
	v_min_u32_e32 v166, 0x100, v166
	v_min_u32_e32 v167, 0x100, v167
	v_min_u32_e32 v168, 0x100, v168
	v_min_u32_e32 v169, 0x100, v169
	v_add_u32_e32 v162, 27, v162
	v_lshl_add_u32 v163, v163, 2, s20
	v_lshl_add_u32 v164, v164, 2, s20
	v_lshl_add_u32 v165, v165, 2, s20
	v_lshl_add_u32 v166, v166, 2, s20
	v_lshl_add_u32 v167, v167, 2, s20
	v_lshl_add_u32 v168, v168, 2, s20
	v_lshl_add_u32 v169, v169, 2, s20
	v_min_u32_e32 v162, 0x100, v162
	v_lshl_add_u32 v180, v162, 2, s20
	ds_read_b32 v162, v163
	ds_read_b32 v163, v164
	ds_read_b32 v164, v165
	ds_read_b32 v165, v166
	ds_read_b32 v166, v167
	ds_read_b32 v167, v168
	ds_read_b32 v168, v169
	ds_read_b32 v169, v180
	ds_read_b32 v170, v170
	ds_read_b32 v171, v171
	ds_read_b32 v172, v172
	ds_read_b32 v173, v173
	ds_read_b32 v174, v174
	ds_read_b32 v175, v175
	ds_read_b32 v176, v176
	ds_read_b32 v177, v177
	s_waitcnt lgkmcnt(0)
	v_pk_add_f32 v[144:145], v[144:145], v[168:169]
	v_pk_add_f32 v[142:143], v[142:143], v[166:167]
	v_pk_add_f32 v[140:141], v[140:141], v[164:165]
	v_pk_add_f32 v[138:139], v[138:139], v[162:163]
	v_pk_add_f32 v[136:137], v[136:137], v[176:177]
	v_pk_add_f32 v[134:135], v[134:135], v[174:175]
	v_pk_add_f32 v[132:133], v[132:133], v[172:173]
	v_pk_add_f32 v[130:131], v[130:131], v[170:171]
	s_mov_b32 s22, 0

; #define SBAR() __builtin_amdgcn_sched_barrier(0)
; template <int D0, int S> __device__ __forceinline__ VG vload(ldsc_t vb) { VG g; g.l0 = vtr(vb + v_rd_off(D0, 2 * S, 0)); g.h0 = vtr(vb + v_rd_off(D0, 2 * S, 1)); g.l1 = vtr(vb + v_rd_off(D0, 2 * S + 1, 0)); g.h1 = vtr(vb + v_rd_off(D0, 2 * S + 1, 1)); return g; }
; __device__ __forceinline__ void softmax_sub(f32x16& p, float& m_reg, float& l_reg, bf16x8& pa0, bf16x8& pa1, f32x16 (&o)[8], float* al_l, int r32, int hi, int dj, const float* tab, float cL, float cR) {
;     ...
;   const float mnC = (cb - mn) * C;
;   float ps = 0;
; #pragma unroll
;   for (int r = 0; r < 16; ++r) { p[r] = __builtin_amdgcn_exp2f(fmaf(p[r], C, mnC)); ps += p[r]; }
;   { auto rr = __builtin_amdgcn_permlane32_swap(__float_as_uint(ps), __float_as_uint(ps), false, false);
;     ps = __uint_as_float(rr[0]) + __uint_as_float(rr[1]); }
;   l_reg = l_reg * alpha + ps;
;     ...
;   PK4(p, 0, pa0); PK4(p, 8, pa1);
;     ...
; }
; template <int S, class Dma> __device__ __forceinline__ void pv_run(f32x16 (&o)[8], ldsc_t vb, VG g0, VG g1, bf16x8 pa0, bf16x8 pa1, const Dma& dma) {
;   SBAR(); __builtin_amdgcn_s_setprio(1);
;   vmma(o[0], g0, pa0, pa1); dma(0); SBAR(); g0 = vload<2, S>(vb); SBAR();
;   vmma(o[1], g1, pa0, pa1); dma(1); SBAR(); g1 = vload<3, S>(vb); SBAR();
;   vmma(o[2], g0, pa0, pa1); dma(2); SBAR(); g0 = vload<4, S>(vb); SBAR();
;   vmma(o[3], g1, pa0, pa1); dma(3); SBAR(); g1 = vload<5, S>(vb); SBAR();
;   vmma(o[4], g0, pa0, pa1); dma(4); SBAR(); g0 = vload<6, S>(vb); SBAR();
;   vmma(o[5], g1, pa0, pa1); dma(5); SBAR(); g1 = vload<7, S>(vb); SBAR();
;   vmma(o[6], g0, pa0, pa1); dma(6); SBAR(); vmma(o[7], g1, pa0, pa1); dma(7); __builtin_amdgcn_s_setprio(0); SBAR();
.LBB0_582:
	v_sub_f32_e32 v162, s19, v181
	v_mul_f32_e32 v162, 0x3e0293ee, v162
	v_fmamk_f32 v130, v130, 0x3e0293ee, v162
	v_exp_f32_e32 v163, v130
	v_fmamk_f32 v130, v131, 0x3e0293ee, v162
	v_exp_f32_e32 v164, v130
	v_fmamk_f32 v130, v132, 0x3e0293ee, v162
	v_exp_f32_e32 v165, v130
	v_fmamk_f32 v130, v133, 0x3e0293ee, v162
	v_exp_f32_e32 v133, v130
	v_fmamk_f32 v131, v134, 0x3e0293ee, v162
	v_add_f32_e32 v130, 0, v163
	v_exp_f32_e32 v134, v131
	v_fmamk_f32 v131, v135, 0x3e0293ee, v162
	v_add_f32_e32 v130, v164, v130
	v_exp_f32_e32 v135, v131
	v_fmamk_f32 v131, v136, 0x3e0293ee, v162
	v_add_f32_e32 v130, v165, v130
	v_exp_f32_e32 v136, v131
	v_fmamk_f32 v131, v137, 0x3e0293ee, v162
	v_add_f32_e32 v130, v133, v130
	v_exp_f32_e32 v137, v131
	v_fmamk_f32 v131, v138, 0x3e0293ee, v162
	v_add_f32_e32 v130, v134, v130
	v_exp_f32_e32 v138, v131
	v_fmamk_f32 v131, v139, 0x3e0293ee, v162
	v_add_f32_e32 v130, v135, v130
	v_exp_f32_e32 v139, v131
	v_fmamk_f32 v131, v140, 0x3e0293ee, v162
	v_add_f32_e32 v130, v136, v130
	v_exp_f32_e32 v140, v131
	v_fmamk_f32 v131, v141, 0x3e0293ee, v162
	v_add_f32_e32 v130, v137, v130
	v_exp_f32_e32 v141, v131
	v_fmamk_f32 v131, v142, 0x3e0293ee, v162
	v_add_f32_e32 v130, v138, v130
	v_exp_f32_e32 v142, v131
	v_fmamk_f32 v131, v143, 0x3e0293ee, v162
	v_add_f32_e32 v130, v139, v130
	v_exp_f32_e32 v143, v131
	v_fmamk_f32 v131, v144, 0x3e0293ee, v162
	v_add_f32_e32 v130, v140, v130
	v_exp_f32_e32 v144, v131
	v_fmac_f32_e32 v162, 0x3e0293ee, v145
	v_add_f32_e32 v130, v141, v130
	v_exp_f32_e32 v145, v162
	v_add_f32_e32 v130, v142, v130
	v_add_f32_e32 v130, v143, v130
	v_add_f32_e32 v130, v144, v130
	v_add_f32_e32 v130, v145, v130
	v_mov_b32_e32 v131, v130
	s_nop 1
	v_permlane32_swap_b32_e32 v130, v131
	v_cvt_pk_bf16_f32 v132, v163, v164
	v_cvt_pk_bf16_f32 v133, v165, v133
	v_cvt_pk_bf16_f32 v134, v134, v135
	v_cvt_pk_bf16_f32 v135, v136, v137
	v_cvt_pk_bf16_f32 v136, v138, v139
	v_cvt_pk_bf16_f32 v137, v140, v141
	v_cvt_pk_bf16_f32 v138, v142, v143
	v_cvt_pk_bf16_f32 v139, v144, v145
	s_nop 0
	v_permlane32_swap_b32_e32 v132, v134
	v_permlane32_swap_b32_e32 v133, v135
	v_permlane32_swap_b32_e32 v136, v138
	v_permlane32_swap_b32_e32 v137, v139
	s_waitcnt vmcnt(4)
	s_barrier
	s_setprio 1
	s_waitcnt lgkmcnt(0)
	v_mfma_f32_32x32x16_bf16 v[98:113], v[132:135], v[154:157], v[98:113]
	v_mfma_f32_32x32x16_bf16 v[98:113], v[136:139], v[158:161], v[98:113]
	ds_read_b64_tr_b16 v[140:141], v1 offset:50176
	ds_read_b64_tr_b16 v[142:143], v1 offset:54272
	ds_read_b64_tr_b16 v[154:155], v1 offset:58368
	ds_read_b64_tr_b16 v[156:157], v1 offset:62464
	v_mfma_f32_32x32x16_bf16 v[114:129], v[132:135], v[150:153], v[114:129]
	v_mfma_f32_32x32x16_bf16 v[114:129], v[136:139], v[146:149], v[114:129]
	ds_read_b64_tr_b16 v[144:145], v1 offset:50688
	ds_read_b64_tr_b16 v[146:147], v1 offset:54784
	ds_read_b64_tr_b16 v[148:149], v1 offset:58880
	ds_read_b64_tr_b16 v[150:151], v1 offset:62976
	s_waitcnt lgkmcnt(4)
	v_mfma_f32_32x32x16_bf16 v[66:81], v[132:135], v[140:143], v[66:81]
	v_mfma_f32_32x32x16_bf16 v[66:81], v[136:139], v[154:157], v[66:81]
	ds_read_b64_tr_b16 v[140:141], v1 offset:51200
	ds_read_b64_tr_b16 v[142:143], v1 offset:55296
	ds_read_b64_tr_b16 v[152:153], v1 offset:59392
	ds_read_b64_tr_b16 v[154:155], v1 offset:63488
	s_waitcnt lgkmcnt(4)
	v_mfma_f32_32x32x16_bf16 v[82:97], v[132:135], v[144:147], v[82:97]
	v_mfma_f32_32x32x16_bf16 v[82:97], v[136:139], v[148:151], v[82:97]
	ds_read_b64_tr_b16 v[144:145], v1 offset:51712
	ds_read_b64_tr_b16 v[146:147], v1 offset:55808
	ds_read_b64_tr_b16 v[148:149], v1 offset:59904
	ds_read_b64_tr_b16 v[150:151], v1 offset:64000
	s_waitcnt lgkmcnt(4)
	v_mfma_f32_32x32x16_bf16 v[34:49], v[132:135], v[140:143], v[34:49]
	v_mfma_f32_32x32x16_bf16 v[34:49], v[136:139], v[152:155], v[34:49]
	ds_read_b64_tr_b16 v[140:141], v1 offset:52224
	ds_read_b64_tr_b16 v[142:143], v1 offset:56320
	ds_read_b64_tr_b16 v[152:153], v1 offset:60416
	ds_read_b64_tr_b16 v[154:155], v1 offset:64512
	s_waitcnt lgkmcnt(4)
	v_mfma_f32_32x32x16_bf16 v[50:65], v[132:135], v[144:147], v[50:65]
	v_mfma_f32_32x32x16_bf16 v[50:65], v[136:139], v[148:151], v[50:65]
	ds_read_b64_tr_b16 v[144:145], v1 offset:52736
	ds_read_b64_tr_b16 v[146:147], v1 offset:56832
	ds_read_b64_tr_b16 v[148:149], v1 offset:60928
	ds_read_b64_tr_b16 v[150:151], v1 offset:65024
	s_waitcnt lgkmcnt(4)
	v_mfma_f32_32x32x16_bf16 v[18:33], v[132:135], v[140:143], v[18:33]
	v_mfma_f32_32x32x16_bf16 v[18:33], v[136:139], v[152:155], v[18:33]
	s_waitcnt lgkmcnt(0)
	v_mfma_f32_32x32x16_bf16 v[2:17], v[132:135], v[144:147], v[2:17]
	v_mfma_f32_32x32x16_bf16 v[2:17], v[136:139], v[148:151], v[2:17]
	s_setprio 0
	s_cmp_lt_u32 s18, 0x20600
	s_cbranch_scc0 .Lpp_skip_x
	s_barrier
; __device__ __forceinline__ int crow(int r, int hi) { return (r & 3) + 8 * (r >> 2) + 4 * hi; }
; __device__ __forceinline__ void attn_unit(const bf16* __restrict__ qkvb, int seq, int q0, int h, ldsp_t ldsb, float* wsc, const float* tab, float lam) {
;     ...
;   if (hi == 0) li_l[r32] = l_reg; asm volatile("s_waitcnt lgkmcnt(0)" ::: "memory");
;   float rli[16];
; #pragma unroll
;   for (int r = 0; r < 16; ++r) rli[r] = __builtin_amdgcn_rcpf(li_l[crow(r, hi)]);
;   typedef __attribute__((address_space(3))) float* ldsf_t;
;   const ldsf_t df = (ldsf_t)ldsb + (rg * 32 + 4 * hi) * 256;
;   asm volatile("s_waitcnt lgkmcnt(0)" ::: "memory"); __builtin_amdgcn_s_barrier(); asm volatile("" ::: "memory");
;   if (mapw) {
; #pragma unroll
;     for (int r = 0; r < 16; ++r)
; #pragma unroll
;       for (int d = 0; d < 8; ++d) df[((r & 3) + 8 * (r >> 2)) * 256 + ((d * 32 + r32) ^ ((d >> 1) << 2) ^ ((r & 3) << 4))] = -lam * o[d][r] * rli[r];
.Lpp_skip_x:
	s_and_saveexec_b64 s[4:5], vcc
	v_add_f32_e32 v1, v178, v179
	v_fmac_f32_e32 v1, v249, v194
	v_add_f32_e32 v130, v130, v131
	v_fmac_f32_e32 v130, v1, v180
	ds_write_b32 v237, v130
	s_or_b64 exec, exec, s[4:5]
	s_waitcnt lgkmcnt(0)
	v_add_u32_e32 v1, s18, v236
	ds_read_b128 v[130:133], v1
	ds_read_b128 v[134:137], v1 offset:32
	s_lshl_b32 s4, s17, 10
	s_add_i32 s4, s4, 0
	s_cmpk_lt_u32 s16, 0x100
	s_waitcnt lgkmcnt(0)
	v_rcp_f32_e32 v158, v130
	v_rcp_f32_e32 v156, v131
	v_rcp_f32_e32 v155, v132
	v_rcp_f32_e32 v153, v133
	v_rcp_f32_e32 v152, v134
	ds_read_b128 v[130:133], v1 offset:64
	v_rcp_f32_e32 v150, v135
	v_rcp_f32_e32 v149, v136
	v_rcp_f32_e32 v147, v137
	ds_read_b128 v[134:137], v1 offset:96
	s_waitcnt lgkmcnt(0)
	v_rcp_f32_e32 v146, v130
	v_rcp_f32_e32 v144, v131
	v_rcp_f32_e32 v143, v132
	v_rcp_f32_e32 v142, v133
	v_rcp_f32_e32 v141, v134
	v_rcp_f32_e32 v139, v135
	v_rcp_f32_e32 v134, v136
	v_rcp_f32_e32 v130, v137
	v_lshl_add_u32 v1, v248, 12, s4
	s_waitcnt lgkmcnt(0)
	s_barrier
	s_cselect_b64 s[4:5], -1, 0
	v_lshl_add_u32 v159, v247, 2, v1
	v_xor_b32_e32 v131, 4, v247
	v_xor_b32_e32 v132, 8, v247
	v_xor_b32_e32 v133, 12, v247
	v_xor_b32_e32 v135, 16, v247
	v_xor_b32_e32 v140, 20, v247
	v_xor_b32_e32 v145, 24, v247
	v_xor_b32_e32 v148, 28, v247
	s_and_b64 vcc, exec, s[4:5]
	v_lshl_add_u32 v138, v131, 2, v1
	v_lshl_add_u32 v137, v132, 2, v1
	v_lshl_add_u32 v136, v133, 2, v1
	v_lshl_add_u32 v135, v135, 2, v1
	v_lshl_add_u32 v133, v140, 2, v1
	v_lshl_add_u32 v132, v145, 2, v1
	v_lshl_add_u32 v131, v148, 2, v1
	v_add_u32_e32 v157, 0x800, v159
	v_add_u32_e32 v154, 0x2000, v159
	v_add_u32_e32 v151, 0x2800, v159
	v_add_u32_e32 v148, 0x4000, v159
	v_add_u32_e32 v145, 0x4800, v159
	v_add_u32_e32 v1, 0x6000, v159
	v_add_u32_e32 v140, 0x6800, v159
	s_cbranch_vccnz .LBB0_586
	v_mul_f32_e64 v160, v98, -s12
	v_mul_f32_e64 v161, v114, -s12
	v_mul_f32_e32 v160, v160, v158
	v_mul_f32_e32 v161, v161, v158
	ds_write2_b32 v159, v160, v161 offset1:32
	v_mul_f32_e64 v160, v66, -s12
	v_mul_f32_e64 v161, v82, -s12
	v_mul_f32_e32 v160, v160, v158
	v_mul_f32_e32 v161, v161, v158
	ds_write2_b32 v138, v160, v161 offset0:64 offset1:96
	v_mul_f32_e64 v160, v34, -s12
	v_mul_f32_e64 v161, v50, -s12
	v_mul_f32_e32 v160, v160, v158
	v_mul_f32_e32 v161, v161, v158
	ds_write2_b32 v137, v160, v161 offset0:128 offset1:160
	v_mul_f32_e64 v160, v18, -s12
	v_mul_f32_e64 v161, v2, -s12
	v_mul_f32_e32 v160, v160, v158
	v_mul_f32_e32 v161, v161, v158
	ds_write2_b32 v136, v160, v161 offset0:192 offset1:224
	v_mul_f32_e64 v160, v99, -s12
	v_mul_f32_e64 v161, v115, -s12
	v_mul_f32_e32 v160, v160, v156
	v_mul_f32_e32 v161, v161, v156
	v_add_u32_e32 v162, 0x400, v135
	ds_write2_b32 v162, v160, v161 offset1:32
	v_mul_f32_e64 v160, v67, -s12
	v_mul_f32_e64 v161, v83, -s12
	v_mul_f32_e32 v160, v160, v156
	v_mul_f32_e32 v161, v161, v156
	v_add_u32_e32 v162, 0x400, v133
	ds_write2_b32 v162, v160, v161 offset0:64 offset1:96
	v_mul_f32_e64 v160, v35, -s12
	v_mul_f32_e64 v161, v51, -s12
	v_mul_f32_e32 v160, v160, v156
	v_mul_f32_e32 v161, v161, v156
	v_add_u32_e32 v162, 0x400, v132
	ds_write2_b32 v162, v160, v161 offset0:128 offset1:160
	v_mul_f32_e64 v160, v19, -s12
	v_mul_f32_e64 v161, v3, -s12
	v_mul_f32_e32 v160, v160, v156
	v_mul_f32_e32 v161, v161, v156
	v_add_u32_e32 v162, 0x400, v131
	ds_write2_b32 v162, v160, v161 offset0:192 offset1:224
	v_mul_f32_e64 v160, v100, -s12
	v_mul_f32_e64 v161, v116, -s12
	v_mul_f32_e32 v160, v160, v155
	v_mul_f32_e32 v161, v161, v155
	ds_write2_b32 v157, v161, v160 offset1:32
	v_mul_f32_e64 v160, v68, -s12
	v_mul_f32_e64 v161, v84, -s12
	v_mul_f32_e32 v160, v160, v155
	v_mul_f32_e32 v161, v161, v155
	v_add_u32_e32 v162, 0x800, v138
	ds_write2_b32 v162, v161, v160 offset0:64 offset1:96
	v_mul_f32_e64 v160, v36, -s12
	v_mul_f32_e64 v161, v52, -s12
	v_mul_f32_e32 v160, v160, v155
	v_mul_f32_e32 v161, v161, v155
	v_add_u32_e32 v162, 0x800, v137
	ds_write2_b32 v162, v161, v160 offset0:128 offset1:160
	v_mul_f32_e64 v160, v20, -s12
	v_mul_f32_e64 v161, v4, -s12
	v_mul_f32_e32 v160, v160, v155
	v_mul_f32_e32 v161, v161, v155
	v_add_u32_e32 v162, 0x800, v136
	ds_write2_b32 v162, v161, v160 offset0:192 offset1:224
	v_mul_f32_e64 v160, v101, -s12
	v_mul_f32_e64 v161, v117, -s12
	v_mul_f32_e32 v160, v160, v153
	v_mul_f32_e32 v161, v161, v153
	v_add_u32_e32 v162, 0xc00, v135
	ds_write2_b32 v162, v161, v160 offset1:32
	v_mul_f32_e64 v160, v69, -s12
	v_mul_f32_e64 v161, v85, -s12
	v_mul_f32_e32 v160, v160, v153
	v_mul_f32_e32 v161, v161, v153
	v_add_u32_e32 v162, 0xc00, v133
	ds_write2_b32 v162, v161, v160 offset0:64 offset1:96
	v_mul_f32_e64 v160, v37, -s12
	v_mul_f32_e64 v161, v53, -s12
	v_mul_f32_e32 v160, v160, v153
	v_mul_f32_e32 v161, v161, v153
	v_add_u32_e32 v162, 0xc00, v132
	ds_write2_b32 v162, v161, v160 offset0:128 offset1:160
	v_mul_f32_e64 v160, v21, -s12
	v_mul_f32_e64 v161, v5, -s12
	v_mul_f32_e32 v160, v160, v153
	v_mul_f32_e32 v161, v161, v153
	v_add_u32_e32 v162, 0xc00, v131
	ds_write2_b32 v162, v161, v160 offset0:192 offset1:224
	v_mul_f32_e64 v160, v102, -s12
	v_mul_f32_e64 v161, v118, -s12
	v_mul_f32_e32 v160, v160, v152
	v_mul_f32_e32 v161, v161, v152
	ds_write2_b32 v154, v160, v161 offset1:32
	v_mul_f32_e64 v160, v70, -s12
	v_mul_f32_e64 v161, v86, -s12
	v_mul_f32_e32 v160, v160, v152
	v_mul_f32_e32 v161, v161, v152
	v_add_u32_e32 v162, 0x2000, v138
	ds_write2_b32 v162, v160, v161 offset0:64 offset1:96
	v_mul_f32_e64 v160, v38, -s12
	v_mul_f32_e64 v161, v54, -s12
	v_mul_f32_e32 v160, v160, v152
	v_mul_f32_e32 v161, v161, v152
	v_add_u32_e32 v162, 0x2000, v137
	ds_write2_b32 v162, v160, v161 offset0:128 offset1:160
; __device__ __forceinline__ void attn_unit(const bf16* __restrict__ qkvb, int seq, int q0, int h, ldsp_t ldsb, float* wsc, const float* tab, float lam) {
;     ...
;   if (mapw) {
; #pragma unroll
;     for (int r = 0; r < 16; ++r)
; #pragma unroll
;       for (int d = 0; d < 8; ++d) df[((r & 3) + 8 * (r >> 2)) * 256 + ((d * 32 + r32) ^ ((d >> 1) << 2) ^ ((r & 3) << 4))] = -lam * o[d][r] * rli[r];
;   }
	v_mul_f32_e64 v160, v22, -s12
	v_mul_f32_e64 v161, v6, -s12
	v_mul_f32_e32 v160, v160, v152
	v_mul_f32_e32 v161, v161, v152
	v_add_u32_e32 v162, 0x2000, v136
	ds_write2_b32 v162, v160, v161 offset0:192 offset1:224
	v_mul_f32_e64 v160, v103, -s12
	v_mul_f32_e64 v161, v119, -s12
	v_mul_f32_e32 v160, v160, v150
	v_mul_f32_e32 v161, v161, v150
	v_add_u32_e32 v162, 0x2400, v135
	ds_write2_b32 v162, v160, v161 offset1:32
	v_mul_f32_e64 v160, v71, -s12
	v_mul_f32_e64 v161, v87, -s12
	v_mul_f32_e32 v160, v160, v150
	v_mul_f32_e32 v161, v161, v150
	v_add_u32_e32 v162, 0x2400, v133
	ds_write2_b32 v162, v160, v161 offset0:64 offset1:96
	v_mul_f32_e64 v160, v39, -s12
	v_mul_f32_e64 v161, v55, -s12
	v_mul_f32_e32 v160, v160, v150
	v_mul_f32_e32 v161, v161, v150
	v_add_u32_e32 v162, 0x2400, v132
	ds_write2_b32 v162, v160, v161 offset0:128 offset1:160
	v_mul_f32_e64 v160, v23, -s12
	v_mul_f32_e64 v161, v7, -s12
	v_mul_f32_e32 v160, v160, v150
	v_mul_f32_e32 v161, v161, v150
	v_add_u32_e32 v162, 0x2400, v131
	ds_write2_b32 v162, v160, v161 offset0:192 offset1:224
	v_mul_f32_e64 v160, v104, -s12
	v_mul_f32_e64 v161, v120, -s12
	v_mul_f32_e32 v160, v160, v149
	v_mul_f32_e32 v161, v161, v149
	ds_write2_b32 v151, v161, v160 offset1:32
	v_mul_f32_e64 v160, v72, -s12
	v_mul_f32_e64 v161, v88, -s12
	v_mul_f32_e32 v160, v160, v149
	v_mul_f32_e32 v161, v161, v149
	v_add_u32_e32 v162, 0x2800, v138
	ds_write2_b32 v162, v161, v160 offset0:64 offset1:96
	v_mul_f32_e64 v160, v40, -s12
	v_mul_f32_e64 v161, v56, -s12
	v_mul_f32_e32 v160, v160, v149
	v_mul_f32_e32 v161, v161, v149
	v_add_u32_e32 v162, 0x2800, v137
	ds_write2_b32 v162, v161, v160 offset0:128 offset1:160
	v_mul_f32_e64 v160, v24, -s12
	v_mul_f32_e64 v161, v8, -s12
	v_mul_f32_e32 v160, v160, v149
	v_mul_f32_e32 v161, v161, v149
	v_add_u32_e32 v162, 0x2800, v136
	ds_write2_b32 v162, v161, v160 offset0:192 offset1:224
	v_mul_f32_e64 v160, v105, -s12
	v_mul_f32_e64 v161, v121, -s12
	v_mul_f32_e32 v160, v160, v147
	v_mul_f32_e32 v161, v161, v147
	v_add_u32_e32 v162, 0x2c00, v135
	ds_write2_b32 v162, v161, v160 offset1:32
	v_mul_f32_e64 v160, v73, -s12
	v_mul_f32_e64 v161, v89, -s12
	v_mul_f32_e32 v160, v160, v147
	v_mul_f32_e32 v161, v161, v147
	v_add_u32_e32 v162, 0x2c00, v133
	ds_write2_b32 v162, v161, v160 offset0:64 offset1:96
	v_mul_f32_e64 v160, v41, -s12
	v_mul_f32_e64 v161, v57, -s12
	v_mul_f32_e32 v160, v160, v147
	v_mul_f32_e32 v161, v161, v147
	v_add_u32_e32 v162, 0x2c00, v132
	ds_write2_b32 v162, v161, v160 offset0:128 offset1:160
	v_mul_f32_e64 v160, v25, -s12
	v_mul_f32_e64 v161, v9, -s12
	v_mul_f32_e32 v160, v160, v147
	v_mul_f32_e32 v161, v161, v147
	v_add_u32_e32 v162, 0x2c00, v131
	ds_write2_b32 v162, v161, v160 offset0:192 offset1:224
	v_mul_f32_e64 v160, v106, -s12
	v_mul_f32_e64 v161, v122, -s12
	v_mul_f32_e32 v160, v160, v146
	v_mul_f32_e32 v161, v161, v146
	ds_write2_b32 v148, v160, v161 offset1:32
	v_mul_f32_e64 v160, v74, -s12
	v_mul_f32_e64 v161, v90, -s12
	v_mul_f32_e32 v160, v160, v146
	v_mul_f32_e32 v161, v161, v146
	v_add_u32_e32 v162, 0x4000, v138
	ds_write2_b32 v162, v160, v161 offset0:64 offset1:96
	v_mul_f32_e64 v160, v42, -s12
	v_mul_f32_e64 v161, v58, -s12
	v_mul_f32_e32 v160, v160, v146
	v_mul_f32_e32 v161, v161, v146
	v_add_u32_e32 v162, 0x4000, v137
	ds_write2_b32 v162, v160, v161 offset0:128 offset1:160
	v_mul_f32_e64 v160, v26, -s12
	v_mul_f32_e64 v161, v10, -s12
	v_mul_f32_e32 v160, v160, v146
	v_mul_f32_e32 v161, v161, v146
	v_add_u32_e32 v162, 0x4000, v136
	ds_write2_b32 v162, v160, v161 offset0:192 offset1:224
	v_mul_f32_e64 v160, v107, -s12
	v_mul_f32_e64 v161, v123, -s12
	v_mul_f32_e32 v160, v160, v144
	v_mul_f32_e32 v161, v161, v144
	v_add_u32_e32 v162, 0x4400, v135
	ds_write2_b32 v162, v160, v161 offset1:32
	v_mul_f32_e64 v160, v75, -s12
	v_mul_f32_e64 v161, v91, -s12
	v_mul_f32_e32 v160, v160, v144
	v_mul_f32_e32 v161, v161, v144
	v_add_u32_e32 v162, 0x4400, v133
	ds_write2_b32 v162, v160, v161 offset0:64 offset1:96
	v_mul_f32_e64 v160, v43, -s12
	v_mul_f32_e64 v161, v59, -s12
	v_mul_f32_e32 v160, v160, v144
	v_mul_f32_e32 v161, v161, v144
	v_add_u32_e32 v162, 0x4400, v132
	ds_write2_b32 v162, v160, v161 offset0:128 offset1:160
	v_mul_f32_e64 v160, v27, -s12
	v_mul_f32_e64 v161, v11, -s12
	v_mul_f32_e32 v160, v160, v144
	v_mul_f32_e32 v161, v161, v144
	v_add_u32_e32 v162, 0x4400, v131
	ds_write2_b32 v162, v160, v161 offset0:192 offset1:224
	v_mul_f32_e64 v160, v108, -s12
	v_mul_f32_e64 v161, v124, -s12
	v_mul_f32_e32 v160, v160, v143
	v_mul_f32_e32 v161, v161, v143
	ds_write2_b32 v145, v161, v160 offset1:32
	v_mul_f32_e64 v160, v76, -s12
	v_mul_f32_e64 v161, v92, -s12
	v_mul_f32_e32 v160, v160, v143
	v_mul_f32_e32 v161, v161, v143
; __device__ __forceinline__ void attn_unit(const bf16* __restrict__ qkvb, int seq, int q0, int h, ldsp_t ldsb, float* wsc, const float* tab, float lam) {
;     ...
;   if (mapw) {
; #pragma unroll
;     for (int r = 0; r < 16; ++r)
; #pragma unroll
;       for (int d = 0; d < 8; ++d) df[((r & 3) + 8 * (r >> 2)) * 256 + ((d * 32 + r32) ^ ((d >> 1) << 2) ^ ((r & 3) << 4))] = -lam * o[d][r] * rli[r];
;   }
	v_add_u32_e32 v162, 0x4800, v138
	ds_write2_b32 v162, v161, v160 offset0:64 offset1:96
	v_mul_f32_e64 v160, v44, -s12
	v_mul_f32_e64 v161, v60, -s12
	v_mul_f32_e32 v160, v160, v143
	v_mul_f32_e32 v161, v161, v143
	v_add_u32_e32 v162, 0x4800, v137
	ds_write2_b32 v162, v161, v160 offset0:128 offset1:160
	v_mul_f32_e64 v160, v28, -s12
	v_mul_f32_e64 v161, v12, -s12
	v_mul_f32_e32 v160, v160, v143
	v_mul_f32_e32 v161, v161, v143
	v_add_u32_e32 v162, 0x4800, v136
	ds_write2_b32 v162, v161, v160 offset0:192 offset1:224
	v_mul_f32_e64 v160, v109, -s12
	v_mul_f32_e64 v161, v125, -s12
	v_mul_f32_e32 v160, v160, v142
	v_mul_f32_e32 v161, v161, v142
	v_add_u32_e32 v162, 0x4c00, v135
	ds_write2_b32 v162, v161, v160 offset1:32
	v_mul_f32_e64 v160, v77, -s12
	v_mul_f32_e64 v161, v93, -s12
	v_mul_f32_e32 v160, v160, v142
	v_mul_f32_e32 v161, v161, v142
	v_add_u32_e32 v162, 0x4c00, v133
	ds_write2_b32 v162, v161, v160 offset0:64 offset1:96
	v_mul_f32_e64 v160, v45, -s12
	v_mul_f32_e64 v161, v61, -s12
	v_mul_f32_e32 v160, v160, v142
	v_mul_f32_e32 v161, v161, v142
	v_add_u32_e32 v162, 0x4c00, v132
	ds_write2_b32 v162, v161, v160 offset0:128 offset1:160
	v_mul_f32_e64 v160, v29, -s12
	v_mul_f32_e64 v161, v13, -s12
	v_mul_f32_e32 v160, v160, v142
	v_mul_f32_e32 v161, v161, v142
	v_add_u32_e32 v162, 0x4c00, v131
	ds_write2_b32 v162, v161, v160 offset0:192 offset1:224
	v_mul_f32_e64 v160, v110, -s12
	v_mul_f32_e64 v161, v126, -s12
	v_mul_f32_e32 v160, v160, v141
	v_mul_f32_e32 v161, v161, v141
	ds_write2_b32 v1, v160, v161 offset1:32
	v_mul_f32_e64 v160, v78, -s12
	v_mul_f32_e64 v161, v94, -s12
	v_mul_f32_e32 v160, v160, v141
	v_mul_f32_e32 v161, v161, v141
	v_add_u32_e32 v162, 0x6000, v138
	ds_write2_b32 v162, v160, v161 offset0:64 offset1:96
	v_mul_f32_e64 v160, v46, -s12
	v_mul_f32_e64 v161, v62, -s12
	v_mul_f32_e32 v160, v160, v141
	v_mul_f32_e32 v161, v161, v141
	v_add_u32_e32 v162, 0x6000, v137
	ds_write2_b32 v162, v160, v161 offset0:128 offset1:160
	v_mul_f32_e64 v160, v30, -s12
	v_mul_f32_e64 v161, v14, -s12
	v_mul_f32_e32 v160, v160, v141
	v_mul_f32_e32 v161, v161, v141
	v_add_u32_e32 v162, 0x6000, v136
	ds_write2_b32 v162, v160, v161 offset0:192 offset1:224
	v_mul_f32_e64 v160, v111, -s12
	v_mul_f32_e64 v161, v127, -s12
	v_mul_f32_e32 v160, v160, v139
	v_mul_f32_e32 v161, v161, v139
	v_add_u32_e32 v162, 0x6400, v135
	ds_write2_b32 v162, v160, v161 offset1:32
	v_mul_f32_e64 v160, v79, -s12
	v_mul_f32_e64 v161, v95, -s12
	v_mul_f32_e32 v160, v160, v139
	v_mul_f32_e32 v161, v161, v139
	v_add_u32_e32 v162, 0x6400, v133
	ds_write2_b32 v162, v160, v161 offset0:64 offset1:96
	v_mul_f32_e64 v160, v47, -s12
	v_mul_f32_e64 v161, v63, -s12
	v_mul_f32_e32 v160, v160, v139
	v_mul_f32_e32 v161, v161, v139
	v_add_u32_e32 v162, 0x6400, v132
	ds_write2_b32 v162, v160, v161 offset0:128 offset1:160
	v_mul_f32_e64 v160, v31, -s12
	v_mul_f32_e64 v161, v15, -s12
	v_mul_f32_e32 v160, v160, v139
	v_mul_f32_e32 v161, v161, v139
	v_add_u32_e32 v162, 0x6400, v131
	ds_write2_b32 v162, v160, v161 offset0:192 offset1:224
	v_mul_f32_e64 v160, v112, -s12
	v_mul_f32_e64 v161, v128, -s12
	v_mul_f32_e32 v160, v160, v134
	v_mul_f32_e32 v161, v161, v134
	ds_write2_b32 v140, v161, v160 offset1:32
	v_mul_f32_e64 v160, v80, -s12
	v_mul_f32_e64 v161, v96, -s12
	v_mul_f32_e32 v160, v160, v134
	v_mul_f32_e32 v161, v161, v134
	v_add_u32_e32 v162, 0x6800, v138
	ds_write2_b32 v162, v161, v160 offset0:64 offset1:96
	v_mul_f32_e64 v160, v48, -s12
	v_mul_f32_e64 v161, v64, -s12
	v_mul_f32_e32 v160, v160, v134
	v_mul_f32_e32 v161, v161, v134
	v_add_u32_e32 v162, 0x6800, v137
	ds_write2_b32 v162, v161, v160 offset0:128 offset1:160
	v_mul_f32_e64 v160, v32, -s12
	v_mul_f32_e64 v161, v16, -s12
	v_mul_f32_e32 v160, v160, v134
	v_mul_f32_e32 v161, v161, v134
	v_add_u32_e32 v162, 0x6800, v136
	ds_write2_b32 v162, v161, v160 offset0:192 offset1:224
	v_mul_f32_e64 v160, v113, -s12
	v_mul_f32_e64 v161, v129, -s12
	v_mul_f32_e32 v160, v160, v130
	v_mul_f32_e32 v161, v161, v130
	v_add_u32_e32 v162, 0x6c00, v135
	ds_write2_b32 v162, v161, v160 offset1:32
	v_mul_f32_e64 v160, v81, -s12
	v_mul_f32_e64 v161, v97, -s12
	v_mul_f32_e32 v160, v160, v130
	v_mul_f32_e32 v161, v161, v130
	v_add_u32_e32 v162, 0x6c00, v133
	ds_write2_b32 v162, v161, v160 offset0:64 offset1:96
	v_mul_f32_e64 v160, v49, -s12
	v_mul_f32_e64 v161, v65, -s12
	v_mul_f32_e32 v160, v160, v130
	v_mul_f32_e32 v161, v161, v130
	v_add_u32_e32 v162, 0x6c00, v132
	ds_write2_b32 v162, v161, v160 offset0:128 offset1:160
	v_mul_f32_e64 v160, v33, -s12
	v_mul_f32_e64 v161, v17, -s12
	v_mul_f32_e32 v160, v160, v130
	v_mul_f32_e32 v161, v161, v130
	v_add_u32_e32 v162, 0x6c00, v131
	ds_write2_b32 v162, v161, v160 offset0:192 offset1:224
